# in-projection tile epilogue rewritten by hand: all table loads (bias, ssq, gains, rope) issued together up front, ssq quarter loads combined across lanes, in-place kinds per 128-feature half, 16 LDS r
# speedup vs baseline: 1.0868x; 1.0286x over previous
; DI void phaseA_tile(const Params& p0, int l, int ft, int mt, char* lds) {
;     ...
;   const int n0 = ft * 256, m0 = mt * 256;
;   const int tid = get_tid(), lane = tid & 63, wid = tid >> 6, wr = wid >> 2, wc = wid & 3, fr = lane & 15, fq = lane >> 4;
;   const bool is_ctx = m0 >= NLAT;
;   int b, s_base, modrow;
;   if (!is_ctx) { b = m0 / SEQ; s_base = m0 % SEQ; modrow = b; }
;   else { const int c = m0 - NLAT; b = c / CTX; s_base = c % CTX; modrow = 16; }
;   int tl[4];
; #pragma unroll
;   for (int g = 0; g < 4; ++g) tl[g] = (g >> 1) * 128 + wc * 32 + (g & 1) * 16 + fr;
;   f32x4 bvA[2][4];
;   {
;     const float* bb = p.bias + (size_t)(l * 17 + modrow) * INW + n0 + wr * 64 + fq * 4;
; #pragma unroll
;     for (int ai = 0; ai < 2; ++ai)
; #pragma unroll
;       for (int m = 0; m < 4; ++m) bvA[ai][m] = *(const f32x4*)(bb + ai * 128 + m * 16);
;   }
;   float rstd[4];
; #pragma unroll
;   for (int gp = 0; gp < 2; ++gp) {
;     f32x4 sq[2][4];
; #pragma unroll
;     for (int n = 0; n < 2; ++n) {
;       const f32x4* sp = (const f32x4*)(p.ssq + (size_t)(m0 + tl[gp * 2 + n]) * 16);
; #pragma unroll
;       for (int q = 0; q < 4; ++q) sq[n][q] = sp[q];
;     }
; #pragma unroll
;     for (int n = 0; n < 2; ++n) {
;       float ss = 0.f;
; #pragma unroll
;       for (int q = 0; q < 4; ++q) ss += (sq[n][q][0] + sq[n][q][1]) + (sq[n][q][2] + sq[n][q][3]);
;       rstd[gp * 2 + n] = rsqrtf(ss * (1.f / DM) + EPS);
;     }
;   }
; #pragma unroll
;   for (int ai = 0; ai < 2; ++ai) {
;     const int f0 = n0 + ai * 128 + wr * 64;
;     const int hd = f0 >> 6;
;     int kind = 0; const float* gain = p.att_q_gain; bool do_rope = false; bool do_scale = false;
;     bf16_t* vtb = nullptr;
;     if (hd < 8) { kind = 2; gain = p.att_q_gain + l * 64; do_rope = !is_ctx; do_scale = true; }
;     else if (hd < 10) { kind = 2; gain = p.att_k_gain + l * 64; do_rope = !is_ctx; }
;     else if (hd < 12) { kind = 3; vtb = p.VtA + (size_t)((b * 2 + (hd - 10)) * 64) * KEYS; }
;     else if (hd < 20) { kind = 1; }
;     else if (hd < 24) { kind = 0; }
;     else if (hd < 28) { kind = 1; }
;     else if (hd < 32) { kind = 2; gain = p.na_q_gain + l * 64; do_scale = true; }
;     else if (hd < 36) { kind = 2; gain = p.na_k_gain + l * 64; }
;     else if (hd < 40) { kind = 3; vtb = p.VtN + (size_t)((b * 4 + (hd - 36)) * 64) * KEYS; }
;     else { kind = 1; }
.LBB0_356:
	s_or_b64 exec, exec, s[2:3]
	v_readlane_b32 s38, v255, 3
	s_barrier
	s_load_dwordx4 s[12:15], s[80:81], 0x40
	s_load_dwordx4 s[16:19], s[80:81], 0x60
	s_load_dwordx2 s[34:35], s[80:81], 0xb8
	s_load_dwordx4 s[8:11], s[80:81], 0xa8
	s_load_dwordx4 s[4:7], s[80:81], 0xd0
	s_load_dwordx2 s[36:37], s[80:81], 0xe8
	s_lshl_b32 s0, s28, 8
	s_lshl_b32 s30, s68, 8
	s_lshr_b32 s2, s28, 3
	s_sub_i32 s3, s28, 0x80
	s_and_b32 s69, s28, 7
	s_lshl_b32 s69, s69, 8
	s_cmpk_lt_i32 s28, 0x80
	s_cselect_b32 s39, s2, s3
	s_cselect_b32 s2, s2, 16
	s_cselect_b32 s69, s69, 0
	s_cselect_b32 s74, 0, 0x800
	s_cselect_b32 s42, 1, 0
	s_lshl_b32 s3, 1, s68
	s_mov_b32 s40, 1
	s_mov_b32 s41, 1
	s_and_b32 s70, s3, 0x187
	s_cselect_b32 s40, 2, s40
	s_and_b32 s70, s3, 0x200
	s_cselect_b32 s40, 3, s40
	s_and_b32 s70, s3, 0x20
	s_cselect_b32 s40, 0, s40
	s_and_b32 s70, s3, 0x183
	s_cselect_b32 s41, 2, s41
	s_and_b32 s70, s3, 0x204
	s_cselect_b32 s41, 3, s41
	s_and_b32 s70, s3, 0x20
	s_cselect_b32 s41, 0, s41
	s_and_b32 s70, s3, 0x7
	s_cselect_b32 s42, s42, 0
	s_mov_b32 s43, 1.0
	s_and_b32 s70, s3, 0x83
	s_cselect_b32 s43, 0x3e38aa3b, s43
	s_waitcnt lgkmcnt(0)
	s_and_b32 s70, s3, 0x4
	s_cselect_b32 s44, s14, s12
	s_cselect_b32 s45, s15, s13
	s_and_b32 s70, s3, 0x80
	s_cselect_b32 s44, s16, s44
	s_cselect_b32 s45, s17, s45
	s_and_b32 s70, s3, 0x100
	s_cselect_b32 s44, s18, s44
	s_cselect_b32 s45, s19, s45
	s_lshl_b32 s70, s38, 8
	s_add_u32 s44, s44, s70
	s_addc_u32 s45, s45, 0
	s_mul_i32 s3, s38, 17
	s_add_i32 s2, s2, s3
	s_mul_hi_u32 s3, s2, 0x2c00
	s_mul_i32 s2, s2, 0x2c00
	s_add_u32 s4, s4, s2
	s_addc_u32 s5, s5, s3
	s_lshl_b32 s2, s30, 2
	s_add_u32 s4, s4, s2
	s_addc_u32 s5, s5, 0
	s_lshl_b32 s2, s0, 6
	s_add_u32 s36, s36, s2
	s_addc_u32 s37, s37, 0
	s_lshl_b32 s2, s69, 1
	s_add_u32 s46, s6, s2
	s_addc_u32 s47, s7, 0
	v_and_b32_e32 v114, 15, v251
	v_bfe_u32 v115, v251, 4, 2
	v_bfe_u32 v116, v251, 6, 2
	v_lshrrev_b32_e32 v117, 8, v251
	v_lshlrev_b32_e32 v140, 4, v115
	v_lshl_add_u32 v137, v117, 8, v140
	v_lshl_add_u32 v118, v116, 5, v114
	v_lshl_add_u32 v138, v118, 6, v140
	v_add_u32_e32 v139, 0x2000, v138
	v_lshrrev_b32_e32 v119, 1, v116
	v_lshlrev_b32_e32 v120, 5, v115
	v_lshl_add_u32 v141, v119, 7, v120
	v_and_b32_e32 v119, 1, v116
	v_lshl_add_u32 v119, v119, 5, v114
	v_lshl_add_u32 v142, v119, 7, v120
	v_lshrrev_b32_e32 v119, 1, v115
	v_lshl_or_b32 v119, v117, 3, v119
	v_xor_b32_e32 v119, v119, v114
	v_lshlrev_b32_e32 v119, 4, v119
	v_and_b32_e32 v120, 1, v115
	v_lshl_or_b32 v119, v120, 3, v119
	v_lshl_add_u32 v130, v118, 9, v119
	v_xor_b32_e32 v131, 32, v130
	v_xor_b32_e32 v132, 64, v130
	v_xor_b32_e32 v133, 96, v130
	v_and_b32_e32 v119, 3, v114
	v_and_b32_e32 v120, 4, v114
	v_lshl_or_b32 v119, v120, 1, v119
	v_and_b32_e32 v120, 8, v114
	v_lshrrev_b32_e32 v120, 1, v120
	v_or_b32_e32 v119, v119, v120
	v_lshl_add_u32 v119, v116, 5, v119
	v_lshlrev_b32_e32 v119, 1, v119
	v_mul_u32_u24_e32 v120, 0x4800, v115
	v_mul_u32_u24_e32 v121, 0x48000, v117
	v_add3_u32 v134, v119, v120, v121
	v_xor_b32_e32 v135, 16, v240
	v_lshlrev_b32_e32 v135, 2, v135
	v_xor_b32_e32 v136, 32, v240
	v_lshlrev_b32_e32 v136, 2, v136
	global_load_dwordx4 v[34:37], v137, s[4:5] offset:0
	global_load_dwordx4 v[38:41], v137, s[4:5] offset:64
	global_load_dwordx4 v[42:45], v137, s[4:5] offset:128
	global_load_dwordx4 v[46:49], v137, s[4:5] offset:192
	global_load_dwordx4 v[146:149], v137, s[4:5] offset:512
	global_load_dwordx4 v[150:153], v137, s[4:5] offset:576
	global_load_dwordx4 v[154:157], v137, s[4:5] offset:640
	global_load_dwordx4 v[158:161], v137, s[4:5] offset:704
	global_load_dwordx4 v[114:117], v138, s[36:37]
	global_load_dwordx4 v[118:121], v138, s[36:37] offset:1024
	global_load_dwordx4 v[122:125], v139, s[36:37]
	global_load_dwordx4 v[126:129], v139, s[36:37] offset:1024
	global_load_dwordx4 v[194:197], v140, s[44:45]
	global_load_dwordx4 v[198:201], v140, s[44:45] offset:64
	global_load_dwordx4 v[202:205], v140, s[44:45] offset:128
	global_load_dwordx4 v[206:209], v140, s[44:45] offset:192
	global_load_dwordx4 v[210:213], v141, s[46:47] offset:0
	global_load_dwordx4 v[214:217], v141, s[46:47] offset:16
	global_load_dwordx4 v[218:221], v141, s[46:47] offset:256
	global_load_dwordx4 v[222:225], v141, s[46:47] offset:272
	global_load_dwordx4 v[226:229], v142, s[6:7] offset:0
	global_load_dwordx4 v[230:233], v142, s[6:7] offset:16
	global_load_dwordx4 v[234:237], v142, s[6:7] offset:2048
	global_load_dwordx4 v[242:245], v142, s[6:7] offset:2064
	s_waitcnt vmcnt(12)
	v_add_f32_e32 v114, v114, v115
	v_add_f32_e32 v116, v116, v117
	v_add_f32_e32 v118, v118, v119
	v_add_f32_e32 v120, v120, v121
	v_add_f32_e32 v122, v122, v123
	v_add_f32_e32 v124, v124, v125
	v_add_f32_e32 v126, v126, v127
	v_add_f32_e32 v128, v128, v129
	v_add_f32_e32 v143, v114, v116
	v_add_f32_e32 v144, v118, v120
	v_add_f32_e32 v145, v122, v124
	v_add_f32_e32 v239, v126, v128
	ds_bpermute_b32 v114, v135, v143
	ds_bpermute_b32 v115, v135, v144
	ds_bpermute_b32 v116, v135, v145
	ds_bpermute_b32 v117, v135, v239
	s_waitcnt lgkmcnt(0)
	v_add_f32_e32 v143, v143, v114
	v_add_f32_e32 v144, v144, v115
	v_add_f32_e32 v145, v145, v116
	v_add_f32_e32 v239, v239, v117
	ds_bpermute_b32 v114, v136, v143
	ds_bpermute_b32 v115, v136, v144
	ds_bpermute_b32 v116, v136, v145
	ds_bpermute_b32 v117, v136, v239
	s_waitcnt lgkmcnt(0)
; DI float silu_f(float v) { return v * __builtin_amdgcn_rcpf(1.f + __expf(-v)); }
; DI void phaseA_tile(const Params& p0, int l, int ft, int mt, char* lds) {
;     ...
;       rstd[gp * 2 + n] = rsqrtf(ss * (1.f / DM) + EPS);
;     }
;   }
; #pragma unroll
;   for (int ai = 0; ai < 2; ++ai) {
;     const int f0 = n0 + ai * 128 + wr * 64;
;     const int hd = f0 >> 6;
;     int kind = 0; const float* gain = p.att_q_gain; bool do_rope = false; bool do_scale = false;
;     bf16_t* vtb = nullptr;
;     if (hd < 8) { kind = 2; gain = p.att_q_gain + l * 64; do_rope = !is_ctx; do_scale = true; }
;     else if (hd < 10) { kind = 2; gain = p.att_k_gain + l * 64; do_rope = !is_ctx; }
;     else if (hd < 12) { kind = 3; vtb = p.VtA + (size_t)((b * 2 + (hd - 10)) * 64) * KEYS; }
;     else if (hd < 20) { kind = 1; }
;     else if (hd < 24) { kind = 0; }
;     else if (hd < 28) { kind = 1; }
;     else if (hd < 32) { kind = 2; gain = p.na_q_gain + l * 64; do_scale = true; }
;     else if (hd < 36) { kind = 2; gain = p.na_k_gain + l * 64; }
;     else if (hd < 40) { kind = 3; vtb = p.VtN + (size_t)((b * 4 + (hd - 36)) * 64) * KEYS; }
;     else { kind = 1; }
;     f32x4 bv[4];
; #pragma unroll
;     for (int m = 0; m < 4; ++m) bv[m] = bvA[ai][m];
;     const float sc = do_scale ? 0.125f * LOG2E : 1.f;
; #pragma unroll
;     for (int gp = 0; gp < 2; ++gp) {
;       float v[2][4][4];
; #pragma unroll
;       for (int n = 0; n < 2; ++n)
; #pragma unroll
;         for (int m = 0; m < 4; ++m)
; #pragma unroll
;           for (int j = 0; j < 4; ++j) v[n][m][j] = acc[ai][gp][m][n][j] * rstd[gp * 2 + n] + bv[m][j];
;       if (kind == 1) {
; #pragma unroll
;         for (int n = 0; n < 2; ++n)
; #pragma unroll
;           for (int m = 0; m < 4; ++m)
; #pragma unroll
;             for (int j = 0; j < 4; ++j) v[n][m][j] = silu_f(v[n][m][j]);
	v_add_f32_e32 v143, v143, v114
	v_add_f32_e32 v144, v144, v115
	v_add_f32_e32 v145, v145, v116
	v_add_f32_e32 v239, v239, v117
	v_mov_b32_e32 v118, 0x358637bd
	s_mov_b32 s2, 0x3a800000
	s_mov_b32 s3, 0x800000
	v_fma_f32 v143, v143, s2, v118
	v_fma_f32 v144, v144, s2, v118
	v_fma_f32 v145, v145, s2, v118
	v_fma_f32 v239, v239, s2, v118
	v_mul_f32_e32 v119, 0x4b800000, v143
	v_cmp_gt_f32_e32 vcc, s3, v143
	s_nop 1
	v_cndmask_b32_e32 v119, v143, v119, vcc
	v_rsq_f32_e32 v119, v119
	s_nop 0
	v_mul_f32_e32 v0, 0x45800000, v119
	v_cndmask_b32_e32 v0, v119, v0, vcc
	v_mul_f32_e32 v120, 0x4b800000, v144
	v_cmp_gt_f32_e32 vcc, s3, v144
	s_nop 1
	v_cndmask_b32_e32 v120, v144, v120, vcc
	v_rsq_f32_e32 v120, v120
	s_nop 0
	v_mul_f32_e32 v238, 0x45800000, v120
	v_cndmask_b32_e32 v238, v120, v238, vcc
	v_mul_f32_e32 v121, 0x4b800000, v145
	v_cmp_gt_f32_e32 vcc, s3, v145
	s_nop 1
	v_cndmask_b32_e32 v121, v145, v121, vcc
	v_rsq_f32_e32 v121, v121
	s_nop 0
	v_mul_f32_e32 v246, 0x45800000, v121
	v_cndmask_b32_e32 v246, v121, v246, vcc
	v_mul_f32_e32 v122, 0x4b800000, v239
	v_cmp_gt_f32_e32 vcc, s3, v239
	s_nop 1
	v_cndmask_b32_e32 v122, v239, v122, vcc
	v_rsq_f32_e32 v122, v122
	s_nop 0
	v_mul_f32_e32 v248, 0x45800000, v122
	v_cndmask_b32_e32 v248, v122, v248, vcc
	s_mov_b32 s70, 0xbfb8aa3b
	s_mov_b32 s71, 1.0
	v_pk_fma_f32 v[190:191], v[190:191], v[0:1], v[34:35] op_sel_hi:[1,0,1]
	v_pk_fma_f32 v[192:193], v[192:193], v[0:1], v[36:37] op_sel_hi:[1,0,1]
	v_pk_fma_f32 v[186:187], v[186:187], v[0:1], v[38:39] op_sel_hi:[1,0,1]
	v_pk_fma_f32 v[188:189], v[188:189], v[0:1], v[40:41] op_sel_hi:[1,0,1]
	v_pk_fma_f32 v[178:179], v[178:179], v[0:1], v[42:43] op_sel_hi:[1,0,1]
	v_pk_fma_f32 v[180:181], v[180:181], v[0:1], v[44:45] op_sel_hi:[1,0,1]
	v_pk_fma_f32 v[170:171], v[170:171], v[0:1], v[46:47] op_sel_hi:[1,0,1]
	v_pk_fma_f32 v[172:173], v[172:173], v[0:1], v[48:49] op_sel_hi:[1,0,1]
	v_pk_fma_f32 v[182:183], v[182:183], v[238:239], v[34:35] op_sel_hi:[1,0,1]
	v_pk_fma_f32 v[184:185], v[184:185], v[238:239], v[36:37] op_sel_hi:[1,0,1]
	v_pk_fma_f32 v[174:175], v[174:175], v[238:239], v[38:39] op_sel_hi:[1,0,1]
	v_pk_fma_f32 v[176:177], v[176:177], v[238:239], v[40:41] op_sel_hi:[1,0,1]
	v_pk_fma_f32 v[166:167], v[166:167], v[238:239], v[42:43] op_sel_hi:[1,0,1]
	v_pk_fma_f32 v[168:169], v[168:169], v[238:239], v[44:45] op_sel_hi:[1,0,1]
	v_pk_fma_f32 v[162:163], v[162:163], v[238:239], v[46:47] op_sel_hi:[1,0,1]
	v_pk_fma_f32 v[164:165], v[164:165], v[238:239], v[48:49] op_sel_hi:[1,0,1]
	s_cmp_eq_u32 s40, 1
	s_cbranch_scc0 .Lea_n1_00
	v_pk_mul_f32 v[114:115], v[190:191], s[70:71] op_sel_hi:[1,0]
	v_pk_mul_f32 v[116:117], v[192:193], s[70:71] op_sel_hi:[1,0]
	v_pk_mul_f32 v[118:119], v[186:187], s[70:71] op_sel_hi:[1,0]
	v_pk_mul_f32 v[120:121], v[188:189], s[70:71] op_sel_hi:[1,0]
	v_exp_f32_e32 v114, v114
	v_exp_f32_e32 v115, v115
	v_exp_f32_e32 v116, v116
	v_exp_f32_e32 v117, v117
	v_exp_f32_e32 v118, v118
	v_exp_f32_e32 v119, v119
	v_exp_f32_e32 v120, v120
	v_exp_f32_e32 v121, v121
	v_pk_add_f32 v[114:115], v[114:115], s[70:71] op_sel:[0,1] op_sel_hi:[1,1]
	v_pk_add_f32 v[116:117], v[116:117], s[70:71] op_sel:[0,1] op_sel_hi:[1,1]
	v_pk_add_f32 v[118:119], v[118:119], s[70:71] op_sel:[0,1] op_sel_hi:[1,1]
	v_pk_add_f32 v[120:121], v[120:121], s[70:71] op_sel:[0,1] op_sel_hi:[1,1]
	v_rcp_f32_e32 v114, v114
	v_rcp_f32_e32 v115, v115
	v_rcp_f32_e32 v116, v116
	v_rcp_f32_e32 v117, v117
	v_rcp_f32_e32 v118, v118
	v_rcp_f32_e32 v119, v119
	v_rcp_f32_e32 v120, v120
	v_rcp_f32_e32 v121, v121
	s_nop 0
	v_pk_mul_f32 v[190:191], v[190:191], v[114:115]
	v_pk_mul_f32 v[192:193], v[192:193], v[116:117]
	v_pk_mul_f32 v[186:187], v[186:187], v[118:119]
	v_pk_mul_f32 v[188:189], v[188:189], v[120:121]
	v_pk_mul_f32 v[114:115], v[178:179], s[70:71] op_sel_hi:[1,0]
	v_pk_mul_f32 v[116:117], v[180:181], s[70:71] op_sel_hi:[1,0]
	v_pk_mul_f32 v[118:119], v[170:171], s[70:71] op_sel_hi:[1,0]
	v_pk_mul_f32 v[120:121], v[172:173], s[70:71] op_sel_hi:[1,0]
	v_exp_f32_e32 v114, v114
	v_exp_f32_e32 v115, v115
	v_exp_f32_e32 v116, v116
	v_exp_f32_e32 v117, v117
	v_exp_f32_e32 v118, v118
	v_exp_f32_e32 v119, v119
	v_exp_f32_e32 v120, v120
	v_exp_f32_e32 v121, v121
	v_pk_add_f32 v[114:115], v[114:115], s[70:71] op_sel:[0,1] op_sel_hi:[1,1]
	v_pk_add_f32 v[116:117], v[116:117], s[70:71] op_sel:[0,1] op_sel_hi:[1,1]
	v_pk_add_f32 v[118:119], v[118:119], s[70:71] op_sel:[0,1] op_sel_hi:[1,1]
	v_pk_add_f32 v[120:121], v[120:121], s[70:71] op_sel:[0,1] op_sel_hi:[1,1]
	v_rcp_f32_e32 v114, v114
	v_rcp_f32_e32 v115, v115
	v_rcp_f32_e32 v116, v116
	v_rcp_f32_e32 v117, v117
	v_rcp_f32_e32 v118, v118
	v_rcp_f32_e32 v119, v119
	v_rcp_f32_e32 v120, v120
	v_rcp_f32_e32 v121, v121
	s_nop 0
	v_pk_mul_f32 v[178:179], v[178:179], v[114:115]
	v_pk_mul_f32 v[180:181], v[180:181], v[116:117]
	v_pk_mul_f32 v[170:171], v[170:171], v[118:119]
	v_pk_mul_f32 v[172:173], v[172:173], v[120:121]
	v_pk_mul_f32 v[114:115], v[182:183], s[70:71] op_sel_hi:[1,0]
	v_pk_mul_f32 v[116:117], v[184:185], s[70:71] op_sel_hi:[1,0]
	v_pk_mul_f32 v[118:119], v[174:175], s[70:71] op_sel_hi:[1,0]
	v_pk_mul_f32 v[120:121], v[176:177], s[70:71] op_sel_hi:[1,0]
	v_exp_f32_e32 v114, v114
	v_exp_f32_e32 v115, v115
	v_exp_f32_e32 v116, v116
	v_exp_f32_e32 v117, v117
	v_exp_f32_e32 v118, v118
	v_exp_f32_e32 v119, v119
	v_exp_f32_e32 v120, v120
	v_exp_f32_e32 v121, v121
	v_pk_add_f32 v[114:115], v[114:115], s[70:71] op_sel:[0,1] op_sel_hi:[1,1]
	v_pk_add_f32 v[116:117], v[116:117], s[70:71] op_sel:[0,1] op_sel_hi:[1,1]
	v_pk_add_f32 v[118:119], v[118:119], s[70:71] op_sel:[0,1] op_sel_hi:[1,1]
; DI float silu_f(float v) { return v * __builtin_amdgcn_rcpf(1.f + __expf(-v)); }
; DI void phaseA_tile(const Params& p0, int l, int ft, int mt, char* lds) {
;     ...
;       if (kind == 1) {
; #pragma unroll
;         for (int n = 0; n < 2; ++n)
; #pragma unroll
;           for (int m = 0; m < 4; ++m)
; #pragma unroll
;             for (int j = 0; j < 4; ++j) v[n][m][j] = silu_f(v[n][m][j]);
;       } else if (kind == 2) {
;         f32x4 gv[4];
; #pragma unroll
;         for (int m = 0; m < 4; ++m) gv[m] = *(const f32x4*)(gain + m * 16 + fq * 4);
; #pragma unroll
;         for (int n = 0; n < 2; ++n) {
;           float ss = 0.f;
; #pragma unroll
;           for (int m = 0; m < 4; ++m)
; #pragma unroll
;             for (int j = 0; j < 4; ++j) ss += v[n][m][j] * v[n][m][j];
;           ss += __shfl_xor(ss, 16);
;           ss += __shfl_xor(ss, 32);
;           const float rn = rsqrtf(ss * (1.f / 64.f) + EPS) * sc;
; #pragma unroll
;           for (int m = 0; m < 4; ++m)
; #pragma unroll
;             for (int j = 0; j < 4; ++j) v[n][m][j] *= rn * gv[m][j];
	v_pk_add_f32 v[120:121], v[120:121], s[70:71] op_sel:[0,1] op_sel_hi:[1,1]
	v_rcp_f32_e32 v114, v114
	v_rcp_f32_e32 v115, v115
	v_rcp_f32_e32 v116, v116
	v_rcp_f32_e32 v117, v117
	v_rcp_f32_e32 v118, v118
	v_rcp_f32_e32 v119, v119
	v_rcp_f32_e32 v120, v120
	v_rcp_f32_e32 v121, v121
	s_nop 0
	v_pk_mul_f32 v[182:183], v[182:183], v[114:115]
	v_pk_mul_f32 v[184:185], v[184:185], v[116:117]
	v_pk_mul_f32 v[174:175], v[174:175], v[118:119]
	v_pk_mul_f32 v[176:177], v[176:177], v[120:121]
	v_pk_mul_f32 v[114:115], v[166:167], s[70:71] op_sel_hi:[1,0]
	v_pk_mul_f32 v[116:117], v[168:169], s[70:71] op_sel_hi:[1,0]
	v_pk_mul_f32 v[118:119], v[162:163], s[70:71] op_sel_hi:[1,0]
	v_pk_mul_f32 v[120:121], v[164:165], s[70:71] op_sel_hi:[1,0]
	v_exp_f32_e32 v114, v114
	v_exp_f32_e32 v115, v115
	v_exp_f32_e32 v116, v116
	v_exp_f32_e32 v117, v117
	v_exp_f32_e32 v118, v118
	v_exp_f32_e32 v119, v119
	v_exp_f32_e32 v120, v120
	v_exp_f32_e32 v121, v121
	v_pk_add_f32 v[114:115], v[114:115], s[70:71] op_sel:[0,1] op_sel_hi:[1,1]
	v_pk_add_f32 v[116:117], v[116:117], s[70:71] op_sel:[0,1] op_sel_hi:[1,1]
	v_pk_add_f32 v[118:119], v[118:119], s[70:71] op_sel:[0,1] op_sel_hi:[1,1]
	v_pk_add_f32 v[120:121], v[120:121], s[70:71] op_sel:[0,1] op_sel_hi:[1,1]
	v_rcp_f32_e32 v114, v114
	v_rcp_f32_e32 v115, v115
	v_rcp_f32_e32 v116, v116
	v_rcp_f32_e32 v117, v117
	v_rcp_f32_e32 v118, v118
	v_rcp_f32_e32 v119, v119
	v_rcp_f32_e32 v120, v120
	v_rcp_f32_e32 v121, v121
	s_nop 0
	v_pk_mul_f32 v[166:167], v[166:167], v[114:115]
	v_pk_mul_f32 v[168:169], v[168:169], v[116:117]
	v_pk_mul_f32 v[162:163], v[162:163], v[118:119]
	v_pk_mul_f32 v[164:165], v[164:165], v[120:121]
	s_branch .Lea_pack_00
.Lea_n1_00:
	s_cmp_eq_u32 s40, 2
	s_cbranch_scc0 .Lea_n2_00
	v_pk_mul_f32 v[114:115], v[190:191], v[190:191]
	v_pk_fma_f32 v[114:115], v[192:193], v[192:193], v[114:115]
	v_pk_fma_f32 v[114:115], v[186:187], v[186:187], v[114:115]
	v_pk_fma_f32 v[114:115], v[188:189], v[188:189], v[114:115]
	v_pk_fma_f32 v[114:115], v[178:179], v[178:179], v[114:115]
	v_pk_fma_f32 v[114:115], v[180:181], v[180:181], v[114:115]
	v_pk_fma_f32 v[114:115], v[170:171], v[170:171], v[114:115]
	v_pk_fma_f32 v[114:115], v[172:173], v[172:173], v[114:115]
	v_pk_mul_f32 v[116:117], v[182:183], v[182:183]
	v_pk_fma_f32 v[116:117], v[184:185], v[184:185], v[116:117]
	v_pk_fma_f32 v[116:117], v[174:175], v[174:175], v[116:117]
	v_pk_fma_f32 v[116:117], v[176:177], v[176:177], v[116:117]
	v_pk_fma_f32 v[116:117], v[166:167], v[166:167], v[116:117]
	v_pk_fma_f32 v[116:117], v[168:169], v[168:169], v[116:117]
	v_pk_fma_f32 v[116:117], v[162:163], v[162:163], v[116:117]
	v_pk_fma_f32 v[116:117], v[164:165], v[164:165], v[116:117]
	v_add_f32_e32 v114, v114, v115
	v_add_f32_e32 v116, v116, v117
	ds_bpermute_b32 v118, v135, v114
	ds_bpermute_b32 v119, v135, v116
	s_waitcnt lgkmcnt(0)
	v_add_f32_e32 v114, v114, v118
	v_add_f32_e32 v116, v116, v119
	ds_bpermute_b32 v118, v136, v114
	ds_bpermute_b32 v119, v136, v116
	s_waitcnt lgkmcnt(0)
	v_add_f32_e32 v114, v114, v118
	v_add_f32_e32 v116, v116, v119
	v_mov_b32_e32 v120, 0x358637bd
	s_mov_b32 s2, 0x3c800000
	v_fma_f32 v114, v114, s2, v120
	v_fma_f32 v116, v116, s2, v120
	v_mul_f32_e32 v118, 0x4b800000, v114
	v_cmp_gt_f32_e32 vcc, s3, v114
	s_nop 1
	v_cndmask_b32_e32 v118, v114, v118, vcc
	v_rsq_f32_e32 v118, v118
	s_nop 0
	v_mul_f32_e32 v122, 0x45800000, v118
	v_cndmask_b32_e32 v122, v118, v122, vcc
	v_mul_f32_e32 v119, 0x4b800000, v116
	v_cmp_gt_f32_e32 vcc, s3, v116
	s_nop 1
	v_cndmask_b32_e32 v119, v116, v119, vcc
	v_rsq_f32_e32 v119, v119
	s_nop 0
	v_mul_f32_e32 v124, 0x45800000, v119
	v_cndmask_b32_e32 v124, v119, v124, vcc
	v_mul_f32_e32 v122, s43, v122
	v_mul_f32_e32 v124, s43, v124
	s_waitcnt vmcnt(8)
	v_pk_mul_f32 v[126:127], v[194:195], v[122:123] op_sel_hi:[1,0]
	v_pk_mul_f32 v[190:191], v[190:191], v[126:127]
	v_pk_mul_f32 v[126:127], v[196:197], v[122:123] op_sel_hi:[1,0]
	v_pk_mul_f32 v[192:193], v[192:193], v[126:127]
	v_pk_mul_f32 v[126:127], v[198:199], v[122:123] op_sel_hi:[1,0]
	v_pk_mul_f32 v[186:187], v[186:187], v[126:127]
	v_pk_mul_f32 v[126:127], v[200:201], v[122:123] op_sel_hi:[1,0]
	v_pk_mul_f32 v[188:189], v[188:189], v[126:127]
	v_pk_mul_f32 v[126:127], v[202:203], v[122:123] op_sel_hi:[1,0]
	v_pk_mul_f32 v[178:179], v[178:179], v[126:127]
	v_pk_mul_f32 v[126:127], v[204:205], v[122:123] op_sel_hi:[1,0]
	v_pk_mul_f32 v[180:181], v[180:181], v[126:127]
	v_pk_mul_f32 v[126:127], v[206:207], v[122:123] op_sel_hi:[1,0]
	v_pk_mul_f32 v[170:171], v[170:171], v[126:127]
	v_pk_mul_f32 v[126:127], v[208:209], v[122:123] op_sel_hi:[1,0]
	v_pk_mul_f32 v[172:173], v[172:173], v[126:127]
	v_pk_mul_f32 v[126:127], v[194:195], v[124:125] op_sel_hi:[1,0]
	v_pk_mul_f32 v[182:183], v[182:183], v[126:127]
	v_pk_mul_f32 v[126:127], v[196:197], v[124:125] op_sel_hi:[1,0]
	v_pk_mul_f32 v[184:185], v[184:185], v[126:127]
	v_pk_mul_f32 v[126:127], v[198:199], v[124:125] op_sel_hi:[1,0]
	v_pk_mul_f32 v[174:175], v[174:175], v[126:127]
	v_pk_mul_f32 v[126:127], v[200:201], v[124:125] op_sel_hi:[1,0]
	v_pk_mul_f32 v[176:177], v[176:177], v[126:127]
	v_pk_mul_f32 v[126:127], v[202:203], v[124:125] op_sel_hi:[1,0]
	v_pk_mul_f32 v[166:167], v[166:167], v[126:127]
	v_pk_mul_f32 v[126:127], v[204:205], v[124:125] op_sel_hi:[1,0]
	v_pk_mul_f32 v[168:169], v[168:169], v[126:127]
	v_pk_mul_f32 v[126:127], v[206:207], v[124:125] op_sel_hi:[1,0]
	v_pk_mul_f32 v[162:163], v[162:163], v[126:127]
	v_pk_mul_f32 v[126:127], v[208:209], v[124:125] op_sel_hi:[1,0]
	v_pk_mul_f32 v[164:165], v[164:165], v[126:127]
	s_cmp_eq_u32 s42, 0
	s_cbranch_scc1 .Lea_pack_00
; DI void phaseA_tile(const Params& p0, int l, int ft, int mt, char* lds) {
;     ...
;         if (do_rope) {
; #pragma unroll
;           for (int n = 0; n < 2; ++n) {
;             f32x4 cs4[2][2];
;             const int s = s_base + tl[gp * 2 + n];
; #pragma unroll
;             for (int hf = 0; hf < 2; ++hf) {
;               const int pos = hf == 0 ? (s >> 6) : (s & 63);
;               const float* tb = p.rope + (size_t)pos * 32 + fq * 8;
;               cs4[hf][0] = *(const f32x4*)(tb);
;               cs4[hf][1] = *(const f32x4*)(tb + 4);
;             }
; #pragma unroll
;             for (int hf = 0; hf < 2; ++hf)
; #pragma unroll
;               for (int j = 0; j < 4; ++j) {
;                 const float c = cs4[hf][j >> 1][(j & 1) * 2], sn = cs4[hf][j >> 1][(j & 1) * 2 + 1];
;                 const float x1 = v[n][2 * hf][j], x2 = v[n][2 * hf + 1][j];
;                 v[n][2 * hf][j] = x1 * c - x2 * sn;
;                 v[n][2 * hf + 1][j] = x2 * c + x1 * sn;
;               }
;           }
;         }
;       }
;       if (kind == 3) {
; #pragma unroll
;         for (int n = 0; n < 2; ++n) {
;           const int kraw = (is_ctx ? SEQ : 0) + s_base + tl[gp * 2 + n];
;           const int k16 = kraw & 15;
;           const int kidx = (kraw & ~15) | ((k16 & 3) | ((k16 & 4) << 1) | ((k16 & 8) >> 1));
; #pragma unroll
;           for (int m = 0; m < 4; ++m)
; #pragma unroll
;             for (int j = 0; j < 4; ++j) {
;               const int d = m * 16 + fq * 4 + j;
;               const unsigned u = pk2(v[n][m][j], 0.f);
;               vtb[(size_t)d * KEYS + kidx] = (bf16_t)(u & 0xffffu);
;             }
;         }
	s_waitcnt vmcnt(0)
	v_mul_f32_e32 v126, v186, v211
	v_mul_f32_e32 v127, v190, v211
	v_fma_f32 v190, v190, v210, -v126
	v_fma_f32 v186, v186, v210, v127
	v_mul_f32_e32 v126, v187, v213
	v_mul_f32_e32 v127, v191, v213
	v_fma_f32 v191, v191, v212, -v126
	v_fma_f32 v187, v187, v212, v127
	v_mul_f32_e32 v126, v188, v215
	v_mul_f32_e32 v127, v192, v215
	v_fma_f32 v192, v192, v214, -v126
	v_fma_f32 v188, v188, v214, v127
	v_mul_f32_e32 v126, v189, v217
	v_mul_f32_e32 v127, v193, v217
	v_fma_f32 v193, v193, v216, -v126
	v_fma_f32 v189, v189, v216, v127
	v_mul_f32_e32 v126, v170, v227
	v_mul_f32_e32 v127, v178, v227
	v_fma_f32 v178, v178, v226, -v126
	v_fma_f32 v170, v170, v226, v127
	v_mul_f32_e32 v126, v171, v229
	v_mul_f32_e32 v127, v179, v229
	v_fma_f32 v179, v179, v228, -v126
	v_fma_f32 v171, v171, v228, v127
	v_mul_f32_e32 v126, v172, v231
	v_mul_f32_e32 v127, v180, v231
	v_fma_f32 v180, v180, v230, -v126
	v_fma_f32 v172, v172, v230, v127
	v_mul_f32_e32 v126, v173, v233
	v_mul_f32_e32 v127, v181, v233
	v_fma_f32 v181, v181, v232, -v126
	v_fma_f32 v173, v173, v232, v127
	v_mul_f32_e32 v126, v174, v211
	v_mul_f32_e32 v127, v182, v211
	v_fma_f32 v182, v182, v210, -v126
	v_fma_f32 v174, v174, v210, v127
	v_mul_f32_e32 v126, v175, v213
	v_mul_f32_e32 v127, v183, v213
	v_fma_f32 v183, v183, v212, -v126
	v_fma_f32 v175, v175, v212, v127
	v_mul_f32_e32 v126, v176, v215
	v_mul_f32_e32 v127, v184, v215
	v_fma_f32 v184, v184, v214, -v126
	v_fma_f32 v176, v176, v214, v127
	v_mul_f32_e32 v126, v177, v217
	v_mul_f32_e32 v127, v185, v217
	v_fma_f32 v185, v185, v216, -v126
	v_fma_f32 v177, v177, v216, v127
	v_mul_f32_e32 v126, v162, v235
	v_mul_f32_e32 v127, v166, v235
	v_fma_f32 v166, v166, v234, -v126
	v_fma_f32 v162, v162, v234, v127
	v_mul_f32_e32 v126, v163, v237
	v_mul_f32_e32 v127, v167, v237
	v_fma_f32 v167, v167, v236, -v126
	v_fma_f32 v163, v163, v236, v127
	v_mul_f32_e32 v126, v164, v243
	v_mul_f32_e32 v127, v168, v243
	v_fma_f32 v168, v168, v242, -v126
	v_fma_f32 v164, v164, v242, v127
	v_mul_f32_e32 v126, v165, v245
	v_mul_f32_e32 v127, v169, v245
	v_fma_f32 v169, v169, v244, -v126
	v_fma_f32 v165, v165, v244, v127
	s_branch .Lea_pack_00
.Lea_n2_00:
	s_cmp_eq_u32 s40, 3
	s_cbranch_scc0 .Lea_pack_00
	s_lshl_b32 s14, s39, 1
	s_lshl_b32 s15, s39, 2
	s_add_i32 s15, s15, 0
	s_cmp_eq_u32 s68, 2
	s_cselect_b32 s12, s10, s34
	s_cselect_b32 s13, s11, s35
	s_cselect_b32 s14, s14, s15
	s_mul_i32 s15, s14, 0x48000
	s_mul_hi_u32 s14, s14, 0x48000
	s_add_u32 s12, s12, s15
	s_addc_u32 s13, s13, s14
	s_add_i32 s14, s74, s69
	s_lshl_b32 s14, s14, 1
	s_add_u32 s12, s12, s14
	s_addc_u32 s13, s13, 0
	v_cvt_pk_bf16_f32 v114, v190, v191
	v_cvt_pk_bf16_f32 v115, v182, v183
	v_add_u32_e32 v116, 0x0, v134
	v_add_u32_e32 v117, 0x1200, v134
	global_store_short v116, v114, s[12:13]
	global_store_short_d16_hi v117, v114, s[12:13]
	global_store_short v116, v115, s[12:13] offset:32
	global_store_short_d16_hi v117, v115, s[12:13] offset:32
	v_cvt_pk_bf16_f32 v114, v192, v193
	v_cvt_pk_bf16_f32 v115, v184, v185
	v_add_u32_e32 v116, 0x2400, v134
	v_add_u32_e32 v117, 0x3600, v134
	global_store_short v116, v114, s[12:13]
	global_store_short_d16_hi v117, v114, s[12:13]
	global_store_short v116, v115, s[12:13] offset:32
	global_store_short_d16_hi v117, v115, s[12:13] offset:32
	v_cvt_pk_bf16_f32 v114, v186, v187
	v_cvt_pk_bf16_f32 v115, v174, v175
	v_add_u32_e32 v116, 0x12000, v134
	v_add_u32_e32 v117, 0x13200, v134
	global_store_short v116, v114, s[12:13]
	global_store_short_d16_hi v117, v114, s[12:13]
	global_store_short v116, v115, s[12:13] offset:32
	global_store_short_d16_hi v117, v115, s[12:13] offset:32
	v_cvt_pk_bf16_f32 v114, v188, v189
	v_cvt_pk_bf16_f32 v115, v176, v177
	v_add_u32_e32 v116, 0x14400, v134
	v_add_u32_e32 v117, 0x15600, v134
	global_store_short v116, v114, s[12:13]
	global_store_short_d16_hi v117, v114, s[12:13]
	global_store_short v116, v115, s[12:13] offset:32
	global_store_short_d16_hi v117, v115, s[12:13] offset:32
	v_cvt_pk_bf16_f32 v114, v178, v179
	v_cvt_pk_bf16_f32 v115, v166, v167
	v_add_u32_e32 v116, 0x24000, v134
	v_add_u32_e32 v117, 0x25200, v134
	global_store_short v116, v114, s[12:13]
	global_store_short_d16_hi v117, v114, s[12:13]
	global_store_short v116, v115, s[12:13] offset:32
	global_store_short_d16_hi v117, v115, s[12:13] offset:32
	v_cvt_pk_bf16_f32 v114, v180, v181
	v_cvt_pk_bf16_f32 v115, v168, v169
	v_add_u32_e32 v116, 0x26400, v134
	v_add_u32_e32 v117, 0x27600, v134
	global_store_short v116, v114, s[12:13]
	global_store_short_d16_hi v117, v114, s[12:13]
	global_store_short v116, v115, s[12:13] offset:32
	global_store_short_d16_hi v117, v115, s[12:13] offset:32
	v_cvt_pk_bf16_f32 v114, v170, v171
	v_cvt_pk_bf16_f32 v115, v162, v163
	v_add_u32_e32 v116, 0x36000, v134
	v_add_u32_e32 v117, 0x37200, v134
	global_store_short v116, v114, s[12:13]
	global_store_short_d16_hi v117, v114, s[12:13]
	global_store_short v116, v115, s[12:13] offset:32
	global_store_short_d16_hi v117, v115, s[12:13] offset:32
	v_cvt_pk_bf16_f32 v114, v172, v173
	v_cvt_pk_bf16_f32 v115, v164, v165
	v_add_u32_e32 v116, 0x38400, v134
	v_add_u32_e32 v117, 0x39600, v134
	global_store_short v116, v114, s[12:13]
	global_store_short_d16_hi v117, v114, s[12:13]
	global_store_short v116, v115, s[12:13] offset:32
	global_store_short_d16_hi v117, v115, s[12:13] offset:32
	s_branch .Lea_done_00
; DI float silu_f(float v) { return v * __builtin_amdgcn_rcpf(1.f + __expf(-v)); }
; DI void phaseA_tile(const Params& p0, int l, int ft, int mt, char* lds) {
;     ...
;     for (int gp = 0; gp < 2; ++gp) {
;       float v[2][4][4];
; #pragma unroll
;       for (int n = 0; n < 2; ++n)
; #pragma unroll
;         for (int m = 0; m < 4; ++m)
; #pragma unroll
;           for (int j = 0; j < 4; ++j) v[n][m][j] = acc[ai][gp][m][n][j] * rstd[gp * 2 + n] + bv[m][j];
;       if (kind == 1) {
; #pragma unroll
;         for (int n = 0; n < 2; ++n)
; #pragma unroll
;           for (int m = 0; m < 4; ++m)
; #pragma unroll
;             for (int j = 0; j < 4; ++j) v[n][m][j] = silu_f(v[n][m][j]);
;     ...
; #pragma unroll
;         for (int n = 0; n < 2; ++n) {
;           const int tlv = tl[gp * 2 + n];
; #pragma unroll
;           for (int m = 0; m < 4; ++m) {
;             u32x2 o;
;             o[0] = pk2(v[n][m][0], v[n][m][1]);
;             o[1] = pk2(v[n][m][2], v[n][m][3]);
;             const int fl = ai * 128 + wr * 64 + m * 16 + fq * 4;
;             *(u32x2*)(lds + tlv * 512 + (((fl >> 3) ^ (tlv & 31)) << 4) + ((fl >> 2) & 1) * 8) = o;
;           }
;         }
;       }
.Lea_pack_00:
	v_cvt_pk_bf16_f32 v190, v190, v191
	v_cvt_pk_bf16_f32 v191, v192, v193
	v_cvt_pk_bf16_f32 v186, v186, v187
	v_cvt_pk_bf16_f32 v187, v188, v189
	v_cvt_pk_bf16_f32 v178, v178, v179
	v_cvt_pk_bf16_f32 v179, v180, v181
	v_cvt_pk_bf16_f32 v170, v170, v171
	v_cvt_pk_bf16_f32 v171, v172, v173
	v_cvt_pk_bf16_f32 v182, v182, v183
	v_cvt_pk_bf16_f32 v183, v184, v185
	v_cvt_pk_bf16_f32 v174, v174, v175
	v_cvt_pk_bf16_f32 v175, v176, v177
	v_cvt_pk_bf16_f32 v166, v166, v167
	v_cvt_pk_bf16_f32 v167, v168, v169
	v_cvt_pk_bf16_f32 v162, v162, v163
	v_cvt_pk_bf16_f32 v163, v164, v165
	ds_write_b64 v130, v[190:191]
	ds_write_b64 v131, v[186:187]
	ds_write_b64 v132, v[178:179]
	ds_write_b64 v133, v[170:171]
	ds_write_b64 v130, v[182:183] offset:8448
	ds_write_b64 v131, v[174:175] offset:8448
	ds_write_b64 v132, v[166:167] offset:8448
	ds_write_b64 v133, v[162:163] offset:8448
.Lea_done_00:
	v_pk_fma_f32 v[78:79], v[78:79], v[0:1], v[146:147] op_sel_hi:[1,0,1]
	v_pk_fma_f32 v[80:81], v[80:81], v[0:1], v[148:149] op_sel_hi:[1,0,1]
	v_pk_fma_f32 v[74:75], v[74:75], v[0:1], v[150:151] op_sel_hi:[1,0,1]
	v_pk_fma_f32 v[76:77], v[76:77], v[0:1], v[152:153] op_sel_hi:[1,0,1]
	v_pk_fma_f32 v[66:67], v[66:67], v[0:1], v[154:155] op_sel_hi:[1,0,1]
	v_pk_fma_f32 v[68:69], v[68:69], v[0:1], v[156:157] op_sel_hi:[1,0,1]
	v_pk_fma_f32 v[58:59], v[58:59], v[0:1], v[158:159] op_sel_hi:[1,0,1]
	v_pk_fma_f32 v[60:61], v[60:61], v[0:1], v[160:161] op_sel_hi:[1,0,1]
	v_pk_fma_f32 v[70:71], v[70:71], v[238:239], v[146:147] op_sel_hi:[1,0,1]
	v_pk_fma_f32 v[72:73], v[72:73], v[238:239], v[148:149] op_sel_hi:[1,0,1]
	v_pk_fma_f32 v[62:63], v[62:63], v[238:239], v[150:151] op_sel_hi:[1,0,1]
	v_pk_fma_f32 v[64:65], v[64:65], v[238:239], v[152:153] op_sel_hi:[1,0,1]
	v_pk_fma_f32 v[54:55], v[54:55], v[238:239], v[154:155] op_sel_hi:[1,0,1]
	v_pk_fma_f32 v[56:57], v[56:57], v[238:239], v[156:157] op_sel_hi:[1,0,1]
	v_pk_fma_f32 v[50:51], v[50:51], v[238:239], v[158:159] op_sel_hi:[1,0,1]
	v_pk_fma_f32 v[52:53], v[52:53], v[238:239], v[160:161] op_sel_hi:[1,0,1]
	s_cmp_eq_u32 s41, 1
	s_cbranch_scc0 .Lea_n1_10
	v_pk_mul_f32 v[114:115], v[78:79], s[70:71] op_sel_hi:[1,0]
	v_pk_mul_f32 v[116:117], v[80:81], s[70:71] op_sel_hi:[1,0]
	v_pk_mul_f32 v[118:119], v[74:75], s[70:71] op_sel_hi:[1,0]
	v_pk_mul_f32 v[120:121], v[76:77], s[70:71] op_sel_hi:[1,0]
	v_exp_f32_e32 v114, v114
	v_exp_f32_e32 v115, v115
	v_exp_f32_e32 v116, v116
	v_exp_f32_e32 v117, v117
	v_exp_f32_e32 v118, v118
	v_exp_f32_e32 v119, v119
	v_exp_f32_e32 v120, v120
	v_exp_f32_e32 v121, v121
	v_pk_add_f32 v[114:115], v[114:115], s[70:71] op_sel:[0,1] op_sel_hi:[1,1]
	v_pk_add_f32 v[116:117], v[116:117], s[70:71] op_sel:[0,1] op_sel_hi:[1,1]
	v_pk_add_f32 v[118:119], v[118:119], s[70:71] op_sel:[0,1] op_sel_hi:[1,1]
	v_pk_add_f32 v[120:121], v[120:121], s[70:71] op_sel:[0,1] op_sel_hi:[1,1]
	v_rcp_f32_e32 v114, v114
	v_rcp_f32_e32 v115, v115
	v_rcp_f32_e32 v116, v116
	v_rcp_f32_e32 v117, v117
	v_rcp_f32_e32 v118, v118
	v_rcp_f32_e32 v119, v119
	v_rcp_f32_e32 v120, v120
	v_rcp_f32_e32 v121, v121
	s_nop 0
	v_pk_mul_f32 v[78:79], v[78:79], v[114:115]
	v_pk_mul_f32 v[80:81], v[80:81], v[116:117]
	v_pk_mul_f32 v[74:75], v[74:75], v[118:119]
	v_pk_mul_f32 v[76:77], v[76:77], v[120:121]
	v_pk_mul_f32 v[114:115], v[66:67], s[70:71] op_sel_hi:[1,0]
	v_pk_mul_f32 v[116:117], v[68:69], s[70:71] op_sel_hi:[1,0]
	v_pk_mul_f32 v[118:119], v[58:59], s[70:71] op_sel_hi:[1,0]
	v_pk_mul_f32 v[120:121], v[60:61], s[70:71] op_sel_hi:[1,0]
	v_exp_f32_e32 v114, v114
	v_exp_f32_e32 v115, v115
	v_exp_f32_e32 v116, v116
	v_exp_f32_e32 v117, v117
	v_exp_f32_e32 v118, v118
	v_exp_f32_e32 v119, v119
	v_exp_f32_e32 v120, v120
	v_exp_f32_e32 v121, v121
	v_pk_add_f32 v[114:115], v[114:115], s[70:71] op_sel:[0,1] op_sel_hi:[1,1]
	v_pk_add_f32 v[116:117], v[116:117], s[70:71] op_sel:[0,1] op_sel_hi:[1,1]
	v_pk_add_f32 v[118:119], v[118:119], s[70:71] op_sel:[0,1] op_sel_hi:[1,1]
	v_pk_add_f32 v[120:121], v[120:121], s[70:71] op_sel:[0,1] op_sel_hi:[1,1]
	v_rcp_f32_e32 v114, v114
	v_rcp_f32_e32 v115, v115
	v_rcp_f32_e32 v116, v116
	v_rcp_f32_e32 v117, v117
	v_rcp_f32_e32 v118, v118
	v_rcp_f32_e32 v119, v119
	v_rcp_f32_e32 v120, v120
	v_rcp_f32_e32 v121, v121
	s_nop 0
	v_pk_mul_f32 v[66:67], v[66:67], v[114:115]
	v_pk_mul_f32 v[68:69], v[68:69], v[116:117]
	v_pk_mul_f32 v[58:59], v[58:59], v[118:119]
	v_pk_mul_f32 v[60:61], v[60:61], v[120:121]
	v_pk_mul_f32 v[114:115], v[70:71], s[70:71] op_sel_hi:[1,0]
	v_pk_mul_f32 v[116:117], v[72:73], s[70:71] op_sel_hi:[1,0]
	v_pk_mul_f32 v[118:119], v[62:63], s[70:71] op_sel_hi:[1,0]
	v_pk_mul_f32 v[120:121], v[64:65], s[70:71] op_sel_hi:[1,0]
	v_exp_f32_e32 v114, v114
	v_exp_f32_e32 v115, v115
	v_exp_f32_e32 v116, v116
	v_exp_f32_e32 v117, v117
	v_exp_f32_e32 v118, v118
	v_exp_f32_e32 v119, v119
	v_exp_f32_e32 v120, v120
	v_exp_f32_e32 v121, v121
	v_pk_add_f32 v[114:115], v[114:115], s[70:71] op_sel:[0,1] op_sel_hi:[1,1]
	v_pk_add_f32 v[116:117], v[116:117], s[70:71] op_sel:[0,1] op_sel_hi:[1,1]
	v_pk_add_f32 v[118:119], v[118:119], s[70:71] op_sel:[0,1] op_sel_hi:[1,1]
	v_pk_add_f32 v[120:121], v[120:121], s[70:71] op_sel:[0,1] op_sel_hi:[1,1]
	v_rcp_f32_e32 v114, v114
	v_rcp_f32_e32 v115, v115
	v_rcp_f32_e32 v116, v116
	v_rcp_f32_e32 v117, v117
	v_rcp_f32_e32 v118, v118
	v_rcp_f32_e32 v119, v119
	v_rcp_f32_e32 v120, v120
	v_rcp_f32_e32 v121, v121
	s_nop 0
	v_pk_mul_f32 v[70:71], v[70:71], v[114:115]
	v_pk_mul_f32 v[72:73], v[72:73], v[116:117]
	v_pk_mul_f32 v[62:63], v[62:63], v[118:119]
	v_pk_mul_f32 v[64:65], v[64:65], v[120:121]
	v_pk_mul_f32 v[114:115], v[54:55], s[70:71] op_sel_hi:[1,0]
	v_pk_mul_f32 v[116:117], v[56:57], s[70:71] op_sel_hi:[1,0]
	v_pk_mul_f32 v[118:119], v[50:51], s[70:71] op_sel_hi:[1,0]
	v_pk_mul_f32 v[120:121], v[52:53], s[70:71] op_sel_hi:[1,0]
	v_exp_f32_e32 v114, v114
	v_exp_f32_e32 v115, v115
	v_exp_f32_e32 v116, v116
	v_exp_f32_e32 v117, v117
	v_exp_f32_e32 v118, v118
	v_exp_f32_e32 v119, v119
	v_exp_f32_e32 v120, v120
	v_exp_f32_e32 v121, v121
	v_pk_add_f32 v[114:115], v[114:115], s[70:71] op_sel:[0,1] op_sel_hi:[1,1]
	v_pk_add_f32 v[116:117], v[116:117], s[70:71] op_sel:[0,1] op_sel_hi:[1,1]
	v_pk_add_f32 v[118:119], v[118:119], s[70:71] op_sel:[0,1] op_sel_hi:[1,1]
	v_pk_add_f32 v[120:121], v[120:121], s[70:71] op_sel:[0,1] op_sel_hi:[1,1]
	v_rcp_f32_e32 v114, v114
	v_rcp_f32_e32 v115, v115
	v_rcp_f32_e32 v116, v116
	v_rcp_f32_e32 v117, v117
	v_rcp_f32_e32 v118, v118
	v_rcp_f32_e32 v119, v119
	v_rcp_f32_e32 v120, v120
	v_rcp_f32_e32 v121, v121
	s_nop 0
	v_pk_mul_f32 v[54:55], v[54:55], v[114:115]
	v_pk_mul_f32 v[56:57], v[56:57], v[116:117]
	v_pk_mul_f32 v[50:51], v[50:51], v[118:119]
	v_pk_mul_f32 v[52:53], v[52:53], v[120:121]
	s_branch .Lea_pack_10
; DI void phaseA_tile(const Params& p0, int l, int ft, int mt, char* lds) {
;     ...
;       } else if (kind == 2) {
;         f32x4 gv[4];
; #pragma unroll
;         for (int m = 0; m < 4; ++m) gv[m] = *(const f32x4*)(gain + m * 16 + fq * 4);
; #pragma unroll
;         for (int n = 0; n < 2; ++n) {
;           float ss = 0.f;
; #pragma unroll
;           for (int m = 0; m < 4; ++m)
; #pragma unroll
;             for (int j = 0; j < 4; ++j) ss += v[n][m][j] * v[n][m][j];
;           ss += __shfl_xor(ss, 16);
;           ss += __shfl_xor(ss, 32);
;           const float rn = rsqrtf(ss * (1.f / 64.f) + EPS) * sc;
; #pragma unroll
;           for (int m = 0; m < 4; ++m)
; #pragma unroll
;             for (int j = 0; j < 4; ++j) v[n][m][j] *= rn * gv[m][j];
;         }
;         if (do_rope) {
; #pragma unroll
;           for (int n = 0; n < 2; ++n) {
;             f32x4 cs4[2][2];
;             const int s = s_base + tl[gp * 2 + n];
; #pragma unroll
;             for (int hf = 0; hf < 2; ++hf) {
;               const int pos = hf == 0 ? (s >> 6) : (s & 63);
;               const float* tb = p.rope + (size_t)pos * 32 + fq * 8;
;               cs4[hf][0] = *(const f32x4*)(tb);
;               cs4[hf][1] = *(const f32x4*)(tb + 4);
;             }
; #pragma unroll
;             for (int hf = 0; hf < 2; ++hf)
; #pragma unroll
;               for (int j = 0; j < 4; ++j) {
;                 const float c = cs4[hf][j >> 1][(j & 1) * 2], sn = cs4[hf][j >> 1][(j & 1) * 2 + 1];
;                 const float x1 = v[n][2 * hf][j], x2 = v[n][2 * hf + 1][j];
;                 v[n][2 * hf][j] = x1 * c - x2 * sn;
;                 v[n][2 * hf + 1][j] = x2 * c + x1 * sn;
;               }
;           }
;         }
.Lea_n1_10:
	s_cmp_eq_u32 s41, 2
	s_cbranch_scc0 .Lea_n2_10
	v_pk_mul_f32 v[114:115], v[78:79], v[78:79]
	v_pk_fma_f32 v[114:115], v[80:81], v[80:81], v[114:115]
	v_pk_fma_f32 v[114:115], v[74:75], v[74:75], v[114:115]
	v_pk_fma_f32 v[114:115], v[76:77], v[76:77], v[114:115]
	v_pk_fma_f32 v[114:115], v[66:67], v[66:67], v[114:115]
	v_pk_fma_f32 v[114:115], v[68:69], v[68:69], v[114:115]
	v_pk_fma_f32 v[114:115], v[58:59], v[58:59], v[114:115]
	v_pk_fma_f32 v[114:115], v[60:61], v[60:61], v[114:115]
	v_pk_mul_f32 v[116:117], v[70:71], v[70:71]
	v_pk_fma_f32 v[116:117], v[72:73], v[72:73], v[116:117]
	v_pk_fma_f32 v[116:117], v[62:63], v[62:63], v[116:117]
	v_pk_fma_f32 v[116:117], v[64:65], v[64:65], v[116:117]
	v_pk_fma_f32 v[116:117], v[54:55], v[54:55], v[116:117]
	v_pk_fma_f32 v[116:117], v[56:57], v[56:57], v[116:117]
	v_pk_fma_f32 v[116:117], v[50:51], v[50:51], v[116:117]
	v_pk_fma_f32 v[116:117], v[52:53], v[52:53], v[116:117]
	v_add_f32_e32 v114, v114, v115
	v_add_f32_e32 v116, v116, v117
	ds_bpermute_b32 v118, v135, v114
	ds_bpermute_b32 v119, v135, v116
	s_waitcnt lgkmcnt(0)
	v_add_f32_e32 v114, v114, v118
	v_add_f32_e32 v116, v116, v119
	ds_bpermute_b32 v118, v136, v114
	ds_bpermute_b32 v119, v136, v116
	s_waitcnt lgkmcnt(0)
	v_add_f32_e32 v114, v114, v118
	v_add_f32_e32 v116, v116, v119
	v_mov_b32_e32 v120, 0x358637bd
	s_mov_b32 s2, 0x3c800000
	v_fma_f32 v114, v114, s2, v120
	v_fma_f32 v116, v116, s2, v120
	v_mul_f32_e32 v118, 0x4b800000, v114
	v_cmp_gt_f32_e32 vcc, s3, v114
	s_nop 1
	v_cndmask_b32_e32 v118, v114, v118, vcc
	v_rsq_f32_e32 v118, v118
	s_nop 0
	v_mul_f32_e32 v122, 0x45800000, v118
	v_cndmask_b32_e32 v122, v118, v122, vcc
	v_mul_f32_e32 v119, 0x4b800000, v116
	v_cmp_gt_f32_e32 vcc, s3, v116
	s_nop 1
	v_cndmask_b32_e32 v119, v116, v119, vcc
	v_rsq_f32_e32 v119, v119
	s_nop 0
	v_mul_f32_e32 v124, 0x45800000, v119
	v_cndmask_b32_e32 v124, v119, v124, vcc
	v_mul_f32_e32 v122, s43, v122
	v_mul_f32_e32 v124, s43, v124
	s_waitcnt vmcnt(8)
	v_pk_mul_f32 v[126:127], v[194:195], v[122:123] op_sel_hi:[1,0]
	v_pk_mul_f32 v[78:79], v[78:79], v[126:127]
	v_pk_mul_f32 v[126:127], v[196:197], v[122:123] op_sel_hi:[1,0]
	v_pk_mul_f32 v[80:81], v[80:81], v[126:127]
	v_pk_mul_f32 v[126:127], v[198:199], v[122:123] op_sel_hi:[1,0]
	v_pk_mul_f32 v[74:75], v[74:75], v[126:127]
	v_pk_mul_f32 v[126:127], v[200:201], v[122:123] op_sel_hi:[1,0]
	v_pk_mul_f32 v[76:77], v[76:77], v[126:127]
	v_pk_mul_f32 v[126:127], v[202:203], v[122:123] op_sel_hi:[1,0]
	v_pk_mul_f32 v[66:67], v[66:67], v[126:127]
	v_pk_mul_f32 v[126:127], v[204:205], v[122:123] op_sel_hi:[1,0]
	v_pk_mul_f32 v[68:69], v[68:69], v[126:127]
	v_pk_mul_f32 v[126:127], v[206:207], v[122:123] op_sel_hi:[1,0]
	v_pk_mul_f32 v[58:59], v[58:59], v[126:127]
	v_pk_mul_f32 v[126:127], v[208:209], v[122:123] op_sel_hi:[1,0]
	v_pk_mul_f32 v[60:61], v[60:61], v[126:127]
	v_pk_mul_f32 v[126:127], v[194:195], v[124:125] op_sel_hi:[1,0]
	v_pk_mul_f32 v[70:71], v[70:71], v[126:127]
	v_pk_mul_f32 v[126:127], v[196:197], v[124:125] op_sel_hi:[1,0]
	v_pk_mul_f32 v[72:73], v[72:73], v[126:127]
	v_pk_mul_f32 v[126:127], v[198:199], v[124:125] op_sel_hi:[1,0]
	v_pk_mul_f32 v[62:63], v[62:63], v[126:127]
	v_pk_mul_f32 v[126:127], v[200:201], v[124:125] op_sel_hi:[1,0]
	v_pk_mul_f32 v[64:65], v[64:65], v[126:127]
	v_pk_mul_f32 v[126:127], v[202:203], v[124:125] op_sel_hi:[1,0]
	v_pk_mul_f32 v[54:55], v[54:55], v[126:127]
	v_pk_mul_f32 v[126:127], v[204:205], v[124:125] op_sel_hi:[1,0]
	v_pk_mul_f32 v[56:57], v[56:57], v[126:127]
	v_pk_mul_f32 v[126:127], v[206:207], v[124:125] op_sel_hi:[1,0]
	v_pk_mul_f32 v[50:51], v[50:51], v[126:127]
	v_pk_mul_f32 v[126:127], v[208:209], v[124:125] op_sel_hi:[1,0]
	v_pk_mul_f32 v[52:53], v[52:53], v[126:127]
	s_cmp_eq_u32 s42, 0
	s_cbranch_scc1 .Lea_pack_10
	s_waitcnt vmcnt(0)
	v_mul_f32_e32 v126, v74, v211
	v_mul_f32_e32 v127, v78, v211
	v_fma_f32 v78, v78, v210, -v126
	v_fma_f32 v74, v74, v210, v127
	v_mul_f32_e32 v126, v75, v213
	v_mul_f32_e32 v127, v79, v213
	v_fma_f32 v79, v79, v212, -v126
	v_fma_f32 v75, v75, v212, v127
	v_mul_f32_e32 v126, v76, v215
	v_mul_f32_e32 v127, v80, v215
	v_fma_f32 v80, v80, v214, -v126
	v_fma_f32 v76, v76, v214, v127
	v_mul_f32_e32 v126, v77, v217
	v_mul_f32_e32 v127, v81, v217
	v_fma_f32 v81, v81, v216, -v126
	v_fma_f32 v77, v77, v216, v127
	v_mul_f32_e32 v126, v58, v227
	v_mul_f32_e32 v127, v66, v227
	v_fma_f32 v66, v66, v226, -v126
	v_fma_f32 v58, v58, v226, v127
	v_mul_f32_e32 v126, v59, v229
	v_mul_f32_e32 v127, v67, v229
	v_fma_f32 v67, v67, v228, -v126
	v_fma_f32 v59, v59, v228, v127
	v_mul_f32_e32 v126, v60, v231
	v_mul_f32_e32 v127, v68, v231
	v_fma_f32 v68, v68, v230, -v126
	v_fma_f32 v60, v60, v230, v127
	v_mul_f32_e32 v126, v61, v233
	v_mul_f32_e32 v127, v69, v233
	v_fma_f32 v69, v69, v232, -v126
	v_fma_f32 v61, v61, v232, v127
	v_mul_f32_e32 v126, v62, v211
	v_mul_f32_e32 v127, v70, v211
	v_fma_f32 v70, v70, v210, -v126
	v_fma_f32 v62, v62, v210, v127
	v_mul_f32_e32 v126, v63, v213
	v_mul_f32_e32 v127, v71, v213
	v_fma_f32 v71, v71, v212, -v126
	v_fma_f32 v63, v63, v212, v127
	v_mul_f32_e32 v126, v64, v215
	v_mul_f32_e32 v127, v72, v215
	v_fma_f32 v72, v72, v214, -v126
	v_fma_f32 v64, v64, v214, v127
	v_mul_f32_e32 v126, v65, v217
	v_mul_f32_e32 v127, v73, v217
	v_fma_f32 v73, v73, v216, -v126
	v_fma_f32 v65, v65, v216, v127
	v_mul_f32_e32 v126, v50, v235
	v_mul_f32_e32 v127, v54, v235
	v_fma_f32 v54, v54, v234, -v126
	v_fma_f32 v50, v50, v234, v127
	v_mul_f32_e32 v126, v51, v237
	v_mul_f32_e32 v127, v55, v237
	v_fma_f32 v55, v55, v236, -v126
	v_fma_f32 v51, v51, v236, v127
	v_mul_f32_e32 v126, v52, v243
	v_mul_f32_e32 v127, v56, v243
	v_fma_f32 v56, v56, v242, -v126
	v_fma_f32 v52, v52, v242, v127
	v_mul_f32_e32 v126, v53, v245
	v_mul_f32_e32 v127, v57, v245
	v_fma_f32 v57, v57, v244, -v126
	v_fma_f32 v53, v53, v244, v127
	s_branch .Lea_pack_10
; DI void phaseA_tile(const Params& p0, int l, int ft, int mt, char* lds) {
;     ...
;     for (int gp = 0; gp < 2; ++gp) {
;       float v[2][4][4];
; #pragma unroll
;       for (int n = 0; n < 2; ++n)
; #pragma unroll
;         for (int m = 0; m < 4; ++m)
; #pragma unroll
;           for (int j = 0; j < 4; ++j) v[n][m][j] = acc[ai][gp][m][n][j] * rstd[gp * 2 + n] + bv[m][j];
;     ...
;       if (kind == 3) {
; #pragma unroll
;         for (int n = 0; n < 2; ++n) {
;           const int kraw = (is_ctx ? SEQ : 0) + s_base + tl[gp * 2 + n];
;           const int k16 = kraw & 15;
;           const int kidx = (kraw & ~15) | ((k16 & 3) | ((k16 & 4) << 1) | ((k16 & 8) >> 1));
; #pragma unroll
;           for (int m = 0; m < 4; ++m)
; #pragma unroll
;             for (int j = 0; j < 4; ++j) {
;               const int d = m * 16 + fq * 4 + j;
;               const unsigned u = pk2(v[n][m][j], 0.f);
;               vtb[(size_t)d * KEYS + kidx] = (bf16_t)(u & 0xffffu);
;             }
;         }
;       } else {
; #pragma unroll
;         for (int n = 0; n < 2; ++n) {
;           const int tlv = tl[gp * 2 + n];
; #pragma unroll
;           for (int m = 0; m < 4; ++m) {
;             u32x2 o;
;             o[0] = pk2(v[n][m][0], v[n][m][1]);
;             o[1] = pk2(v[n][m][2], v[n][m][3]);
;             const int fl = ai * 128 + wr * 64 + m * 16 + fq * 4;
;             *(u32x2*)(lds + tlv * 512 + (((fl >> 3) ^ (tlv & 31)) << 4) + ((fl >> 2) & 1) * 8) = o;
;           }
;         }
;       }
.Lea_n2_10:
	s_cmp_eq_u32 s41, 3
	s_cbranch_scc0 .Lea_pack_10
	s_lshl_b32 s14, s39, 1
	s_lshl_b32 s15, s39, 2
	s_add_i32 s15, s15, 2
	s_cmp_eq_u32 s68, 2
	s_cselect_b32 s12, s10, s34
	s_cselect_b32 s13, s11, s35
	s_cselect_b32 s14, s14, s15
	s_mul_i32 s15, s14, 0x48000
	s_mul_hi_u32 s14, s14, 0x48000
	s_add_u32 s12, s12, s15
	s_addc_u32 s13, s13, s14
	s_add_i32 s14, s74, s69
	s_lshl_b32 s14, s14, 1
	s_add_u32 s12, s12, s14
	s_addc_u32 s13, s13, 0
	v_cvt_pk_bf16_f32 v114, v78, v79
	v_cvt_pk_bf16_f32 v115, v70, v71
	v_add_u32_e32 v116, 0x0, v134
	v_add_u32_e32 v117, 0x1200, v134
	global_store_short v116, v114, s[12:13]
	global_store_short_d16_hi v117, v114, s[12:13]
	global_store_short v116, v115, s[12:13] offset:32
	global_store_short_d16_hi v117, v115, s[12:13] offset:32
	v_cvt_pk_bf16_f32 v114, v80, v81
	v_cvt_pk_bf16_f32 v115, v72, v73
	v_add_u32_e32 v116, 0x2400, v134
	v_add_u32_e32 v117, 0x3600, v134
	global_store_short v116, v114, s[12:13]
	global_store_short_d16_hi v117, v114, s[12:13]
	global_store_short v116, v115, s[12:13] offset:32
	global_store_short_d16_hi v117, v115, s[12:13] offset:32
	v_cvt_pk_bf16_f32 v114, v74, v75
	v_cvt_pk_bf16_f32 v115, v62, v63
	v_add_u32_e32 v116, 0x12000, v134
	v_add_u32_e32 v117, 0x13200, v134
	global_store_short v116, v114, s[12:13]
	global_store_short_d16_hi v117, v114, s[12:13]
	global_store_short v116, v115, s[12:13] offset:32
	global_store_short_d16_hi v117, v115, s[12:13] offset:32
	v_cvt_pk_bf16_f32 v114, v76, v77
	v_cvt_pk_bf16_f32 v115, v64, v65
	v_add_u32_e32 v116, 0x14400, v134
	v_add_u32_e32 v117, 0x15600, v134
	global_store_short v116, v114, s[12:13]
	global_store_short_d16_hi v117, v114, s[12:13]
	global_store_short v116, v115, s[12:13] offset:32
	global_store_short_d16_hi v117, v115, s[12:13] offset:32
	v_cvt_pk_bf16_f32 v114, v66, v67
	v_cvt_pk_bf16_f32 v115, v54, v55
	v_add_u32_e32 v116, 0x24000, v134
	v_add_u32_e32 v117, 0x25200, v134
	global_store_short v116, v114, s[12:13]
	global_store_short_d16_hi v117, v114, s[12:13]
	global_store_short v116, v115, s[12:13] offset:32
	global_store_short_d16_hi v117, v115, s[12:13] offset:32
	v_cvt_pk_bf16_f32 v114, v68, v69
	v_cvt_pk_bf16_f32 v115, v56, v57
	v_add_u32_e32 v116, 0x26400, v134
	v_add_u32_e32 v117, 0x27600, v134
	global_store_short v116, v114, s[12:13]
	global_store_short_d16_hi v117, v114, s[12:13]
	global_store_short v116, v115, s[12:13] offset:32
	global_store_short_d16_hi v117, v115, s[12:13] offset:32
	v_cvt_pk_bf16_f32 v114, v58, v59
	v_cvt_pk_bf16_f32 v115, v50, v51
	v_add_u32_e32 v116, 0x36000, v134
	v_add_u32_e32 v117, 0x37200, v134
	global_store_short v116, v114, s[12:13]
	global_store_short_d16_hi v117, v114, s[12:13]
	global_store_short v116, v115, s[12:13] offset:32
	global_store_short_d16_hi v117, v115, s[12:13] offset:32
	v_cvt_pk_bf16_f32 v114, v60, v61
	v_cvt_pk_bf16_f32 v115, v52, v53
	v_add_u32_e32 v116, 0x38400, v134
	v_add_u32_e32 v117, 0x39600, v134
	global_store_short v116, v114, s[12:13]
	global_store_short_d16_hi v117, v114, s[12:13]
	global_store_short v116, v115, s[12:13] offset:32
	global_store_short_d16_hi v117, v115, s[12:13] offset:32
	s_branch .Lea_done_10
.Lea_pack_10:
	v_cvt_pk_bf16_f32 v78, v78, v79
	v_cvt_pk_bf16_f32 v79, v80, v81
	v_cvt_pk_bf16_f32 v74, v74, v75
	v_cvt_pk_bf16_f32 v75, v76, v77
	v_cvt_pk_bf16_f32 v66, v66, v67
	v_cvt_pk_bf16_f32 v67, v68, v69
	v_cvt_pk_bf16_f32 v58, v58, v59
	v_cvt_pk_bf16_f32 v59, v60, v61
	v_cvt_pk_bf16_f32 v70, v70, v71
	v_cvt_pk_bf16_f32 v71, v72, v73
	v_cvt_pk_bf16_f32 v62, v62, v63
	v_cvt_pk_bf16_f32 v63, v64, v65
	v_cvt_pk_bf16_f32 v54, v54, v55
	v_cvt_pk_bf16_f32 v55, v56, v57
	v_cvt_pk_bf16_f32 v50, v50, v51
	v_cvt_pk_bf16_f32 v51, v52, v53
	ds_write_b64 v130, v[78:79] offset:256
	ds_write_b64 v131, v[74:75] offset:256
	ds_write_b64 v132, v[66:67] offset:256
	ds_write_b64 v133, v[58:59] offset:256
	ds_write_b64 v130, v[70:71] offset:8192
	ds_write_b64 v131, v[62:63] offset:8192
	ds_write_b64 v132, v[54:55] offset:8192
	ds_write_b64 v133, v[50:51] offset:8192
.Lea_done_10:
	v_pk_fma_f32 v[110:111], v[110:111], v[246:247], v[34:35] op_sel_hi:[1,0,1]
	v_pk_fma_f32 v[112:113], v[112:113], v[246:247], v[36:37] op_sel_hi:[1,0,1]
	v_pk_fma_f32 v[106:107], v[106:107], v[246:247], v[38:39] op_sel_hi:[1,0,1]
	v_pk_fma_f32 v[108:109], v[108:109], v[246:247], v[40:41] op_sel_hi:[1,0,1]
	v_pk_fma_f32 v[98:99], v[98:99], v[246:247], v[42:43] op_sel_hi:[1,0,1]
	v_pk_fma_f32 v[100:101], v[100:101], v[246:247], v[44:45] op_sel_hi:[1,0,1]
	v_pk_fma_f32 v[90:91], v[90:91], v[246:247], v[46:47] op_sel_hi:[1,0,1]
	v_pk_fma_f32 v[92:93], v[92:93], v[246:247], v[48:49] op_sel_hi:[1,0,1]
	v_pk_fma_f32 v[102:103], v[102:103], v[248:249], v[34:35] op_sel_hi:[1,0,1]
	v_pk_fma_f32 v[104:105], v[104:105], v[248:249], v[36:37] op_sel_hi:[1,0,1]
	v_pk_fma_f32 v[94:95], v[94:95], v[248:249], v[38:39] op_sel_hi:[1,0,1]
	v_pk_fma_f32 v[96:97], v[96:97], v[248:249], v[40:41] op_sel_hi:[1,0,1]
	v_pk_fma_f32 v[86:87], v[86:87], v[248:249], v[42:43] op_sel_hi:[1,0,1]
	v_pk_fma_f32 v[88:89], v[88:89], v[248:249], v[44:45] op_sel_hi:[1,0,1]
	v_pk_fma_f32 v[82:83], v[82:83], v[248:249], v[46:47] op_sel_hi:[1,0,1]
	v_pk_fma_f32 v[84:85], v[84:85], v[248:249], v[48:49] op_sel_hi:[1,0,1]
	v_add_u32_e32 v130, 0x10000, v130
	v_add_u32_e32 v131, 0x10000, v131
	v_add_u32_e32 v132, 0x10000, v132
	v_add_u32_e32 v133, 0x10000, v133
	s_cmp_eq_u32 s40, 1
	s_cbranch_scc0 .Lea_n1_01
; DI float silu_f(float v) { return v * __builtin_amdgcn_rcpf(1.f + __expf(-v)); }
; DI void phaseA_tile(const Params& p0, int l, int ft, int mt, char* lds) {
;     ...
;       if (kind == 1) {
; #pragma unroll
;         for (int n = 0; n < 2; ++n)
; #pragma unroll
;           for (int m = 0; m < 4; ++m)
; #pragma unroll
;             for (int j = 0; j < 4; ++j) v[n][m][j] = silu_f(v[n][m][j]);
	v_pk_mul_f32 v[114:115], v[110:111], s[70:71] op_sel_hi:[1,0]
	v_pk_mul_f32 v[116:117], v[112:113], s[70:71] op_sel_hi:[1,0]
	v_pk_mul_f32 v[118:119], v[106:107], s[70:71] op_sel_hi:[1,0]
	v_pk_mul_f32 v[120:121], v[108:109], s[70:71] op_sel_hi:[1,0]
	v_exp_f32_e32 v114, v114
	v_exp_f32_e32 v115, v115
	v_exp_f32_e32 v116, v116
	v_exp_f32_e32 v117, v117
	v_exp_f32_e32 v118, v118
	v_exp_f32_e32 v119, v119
	v_exp_f32_e32 v120, v120
	v_exp_f32_e32 v121, v121
	v_pk_add_f32 v[114:115], v[114:115], s[70:71] op_sel:[0,1] op_sel_hi:[1,1]
	v_pk_add_f32 v[116:117], v[116:117], s[70:71] op_sel:[0,1] op_sel_hi:[1,1]
	v_pk_add_f32 v[118:119], v[118:119], s[70:71] op_sel:[0,1] op_sel_hi:[1,1]
	v_pk_add_f32 v[120:121], v[120:121], s[70:71] op_sel:[0,1] op_sel_hi:[1,1]
	v_rcp_f32_e32 v114, v114
	v_rcp_f32_e32 v115, v115
	v_rcp_f32_e32 v116, v116
	v_rcp_f32_e32 v117, v117
	v_rcp_f32_e32 v118, v118
	v_rcp_f32_e32 v119, v119
	v_rcp_f32_e32 v120, v120
	v_rcp_f32_e32 v121, v121
	s_nop 0
	v_pk_mul_f32 v[110:111], v[110:111], v[114:115]
	v_pk_mul_f32 v[112:113], v[112:113], v[116:117]
	v_pk_mul_f32 v[106:107], v[106:107], v[118:119]
	v_pk_mul_f32 v[108:109], v[108:109], v[120:121]
	v_pk_mul_f32 v[114:115], v[98:99], s[70:71] op_sel_hi:[1,0]
	v_pk_mul_f32 v[116:117], v[100:101], s[70:71] op_sel_hi:[1,0]
	v_pk_mul_f32 v[118:119], v[90:91], s[70:71] op_sel_hi:[1,0]
	v_pk_mul_f32 v[120:121], v[92:93], s[70:71] op_sel_hi:[1,0]
	v_exp_f32_e32 v114, v114
	v_exp_f32_e32 v115, v115
	v_exp_f32_e32 v116, v116
	v_exp_f32_e32 v117, v117
	v_exp_f32_e32 v118, v118
	v_exp_f32_e32 v119, v119
	v_exp_f32_e32 v120, v120
	v_exp_f32_e32 v121, v121
	v_pk_add_f32 v[114:115], v[114:115], s[70:71] op_sel:[0,1] op_sel_hi:[1,1]
	v_pk_add_f32 v[116:117], v[116:117], s[70:71] op_sel:[0,1] op_sel_hi:[1,1]
	v_pk_add_f32 v[118:119], v[118:119], s[70:71] op_sel:[0,1] op_sel_hi:[1,1]
	v_pk_add_f32 v[120:121], v[120:121], s[70:71] op_sel:[0,1] op_sel_hi:[1,1]
	v_rcp_f32_e32 v114, v114
	v_rcp_f32_e32 v115, v115
	v_rcp_f32_e32 v116, v116
	v_rcp_f32_e32 v117, v117
	v_rcp_f32_e32 v118, v118
	v_rcp_f32_e32 v119, v119
	v_rcp_f32_e32 v120, v120
	v_rcp_f32_e32 v121, v121
	s_nop 0
	v_pk_mul_f32 v[98:99], v[98:99], v[114:115]
	v_pk_mul_f32 v[100:101], v[100:101], v[116:117]
	v_pk_mul_f32 v[90:91], v[90:91], v[118:119]
	v_pk_mul_f32 v[92:93], v[92:93], v[120:121]
	v_pk_mul_f32 v[114:115], v[102:103], s[70:71] op_sel_hi:[1,0]
	v_pk_mul_f32 v[116:117], v[104:105], s[70:71] op_sel_hi:[1,0]
	v_pk_mul_f32 v[118:119], v[94:95], s[70:71] op_sel_hi:[1,0]
	v_pk_mul_f32 v[120:121], v[96:97], s[70:71] op_sel_hi:[1,0]
	v_exp_f32_e32 v114, v114
	v_exp_f32_e32 v115, v115
	v_exp_f32_e32 v116, v116
	v_exp_f32_e32 v117, v117
	v_exp_f32_e32 v118, v118
	v_exp_f32_e32 v119, v119
	v_exp_f32_e32 v120, v120
	v_exp_f32_e32 v121, v121
	v_pk_add_f32 v[114:115], v[114:115], s[70:71] op_sel:[0,1] op_sel_hi:[1,1]
	v_pk_add_f32 v[116:117], v[116:117], s[70:71] op_sel:[0,1] op_sel_hi:[1,1]
	v_pk_add_f32 v[118:119], v[118:119], s[70:71] op_sel:[0,1] op_sel_hi:[1,1]
	v_pk_add_f32 v[120:121], v[120:121], s[70:71] op_sel:[0,1] op_sel_hi:[1,1]
	v_rcp_f32_e32 v114, v114
	v_rcp_f32_e32 v115, v115
	v_rcp_f32_e32 v116, v116
	v_rcp_f32_e32 v117, v117
	v_rcp_f32_e32 v118, v118
	v_rcp_f32_e32 v119, v119
	v_rcp_f32_e32 v120, v120
	v_rcp_f32_e32 v121, v121
	s_nop 0
	v_pk_mul_f32 v[102:103], v[102:103], v[114:115]
	v_pk_mul_f32 v[104:105], v[104:105], v[116:117]
	v_pk_mul_f32 v[94:95], v[94:95], v[118:119]
	v_pk_mul_f32 v[96:97], v[96:97], v[120:121]
	v_pk_mul_f32 v[114:115], v[86:87], s[70:71] op_sel_hi:[1,0]
	v_pk_mul_f32 v[116:117], v[88:89], s[70:71] op_sel_hi:[1,0]
	v_pk_mul_f32 v[118:119], v[82:83], s[70:71] op_sel_hi:[1,0]
	v_pk_mul_f32 v[120:121], v[84:85], s[70:71] op_sel_hi:[1,0]
	v_exp_f32_e32 v114, v114
	v_exp_f32_e32 v115, v115
	v_exp_f32_e32 v116, v116
	v_exp_f32_e32 v117, v117
	v_exp_f32_e32 v118, v118
	v_exp_f32_e32 v119, v119
	v_exp_f32_e32 v120, v120
	v_exp_f32_e32 v121, v121
	v_pk_add_f32 v[114:115], v[114:115], s[70:71] op_sel:[0,1] op_sel_hi:[1,1]
	v_pk_add_f32 v[116:117], v[116:117], s[70:71] op_sel:[0,1] op_sel_hi:[1,1]
	v_pk_add_f32 v[118:119], v[118:119], s[70:71] op_sel:[0,1] op_sel_hi:[1,1]
	v_pk_add_f32 v[120:121], v[120:121], s[70:71] op_sel:[0,1] op_sel_hi:[1,1]
	v_rcp_f32_e32 v114, v114
	v_rcp_f32_e32 v115, v115
	v_rcp_f32_e32 v116, v116
	v_rcp_f32_e32 v117, v117
	v_rcp_f32_e32 v118, v118
	v_rcp_f32_e32 v119, v119
	v_rcp_f32_e32 v120, v120
	v_rcp_f32_e32 v121, v121
	s_nop 0
	v_pk_mul_f32 v[86:87], v[86:87], v[114:115]
	v_pk_mul_f32 v[88:89], v[88:89], v[116:117]
	v_pk_mul_f32 v[82:83], v[82:83], v[118:119]
	v_pk_mul_f32 v[84:85], v[84:85], v[120:121]
	s_branch .Lea_pack_01
; DI void phaseA_tile(const Params& p0, int l, int ft, int mt, char* lds) {
;     ...
;       } else if (kind == 2) {
;         f32x4 gv[4];
; #pragma unroll
;         for (int m = 0; m < 4; ++m) gv[m] = *(const f32x4*)(gain + m * 16 + fq * 4);
; #pragma unroll
;         for (int n = 0; n < 2; ++n) {
;           float ss = 0.f;
; #pragma unroll
;           for (int m = 0; m < 4; ++m)
; #pragma unroll
;             for (int j = 0; j < 4; ++j) ss += v[n][m][j] * v[n][m][j];
;           ss += __shfl_xor(ss, 16);
;           ss += __shfl_xor(ss, 32);
;           const float rn = rsqrtf(ss * (1.f / 64.f) + EPS) * sc;
; #pragma unroll
;           for (int m = 0; m < 4; ++m)
; #pragma unroll
;             for (int j = 0; j < 4; ++j) v[n][m][j] *= rn * gv[m][j];
;         }
;         if (do_rope) {
; #pragma unroll
;           for (int n = 0; n < 2; ++n) {
;             f32x4 cs4[2][2];
;             const int s = s_base + tl[gp * 2 + n];
; #pragma unroll
;             for (int hf = 0; hf < 2; ++hf) {
;               const int pos = hf == 0 ? (s >> 6) : (s & 63);
;               const float* tb = p.rope + (size_t)pos * 32 + fq * 8;
;               cs4[hf][0] = *(const f32x4*)(tb);
;               cs4[hf][1] = *(const f32x4*)(tb + 4);
;             }
; #pragma unroll
;             for (int hf = 0; hf < 2; ++hf)
; #pragma unroll
;               for (int j = 0; j < 4; ++j) {
;                 const float c = cs4[hf][j >> 1][(j & 1) * 2], sn = cs4[hf][j >> 1][(j & 1) * 2 + 1];
;                 const float x1 = v[n][2 * hf][j], x2 = v[n][2 * hf + 1][j];
;                 v[n][2 * hf][j] = x1 * c - x2 * sn;
;                 v[n][2 * hf + 1][j] = x2 * c + x1 * sn;
;               }
;           }
;         }
.Lea_n1_01:
	s_cmp_eq_u32 s40, 2
	s_cbranch_scc0 .Lea_n2_01
	v_pk_mul_f32 v[114:115], v[110:111], v[110:111]
	v_pk_fma_f32 v[114:115], v[112:113], v[112:113], v[114:115]
	v_pk_fma_f32 v[114:115], v[106:107], v[106:107], v[114:115]
	v_pk_fma_f32 v[114:115], v[108:109], v[108:109], v[114:115]
	v_pk_fma_f32 v[114:115], v[98:99], v[98:99], v[114:115]
	v_pk_fma_f32 v[114:115], v[100:101], v[100:101], v[114:115]
	v_pk_fma_f32 v[114:115], v[90:91], v[90:91], v[114:115]
	v_pk_fma_f32 v[114:115], v[92:93], v[92:93], v[114:115]
	v_pk_mul_f32 v[116:117], v[102:103], v[102:103]
	v_pk_fma_f32 v[116:117], v[104:105], v[104:105], v[116:117]
	v_pk_fma_f32 v[116:117], v[94:95], v[94:95], v[116:117]
	v_pk_fma_f32 v[116:117], v[96:97], v[96:97], v[116:117]
	v_pk_fma_f32 v[116:117], v[86:87], v[86:87], v[116:117]
	v_pk_fma_f32 v[116:117], v[88:89], v[88:89], v[116:117]
	v_pk_fma_f32 v[116:117], v[82:83], v[82:83], v[116:117]
	v_pk_fma_f32 v[116:117], v[84:85], v[84:85], v[116:117]
	v_add_f32_e32 v114, v114, v115
	v_add_f32_e32 v116, v116, v117
	ds_bpermute_b32 v118, v135, v114
	ds_bpermute_b32 v119, v135, v116
	s_waitcnt lgkmcnt(0)
	v_add_f32_e32 v114, v114, v118
	v_add_f32_e32 v116, v116, v119
	ds_bpermute_b32 v118, v136, v114
	ds_bpermute_b32 v119, v136, v116
	s_waitcnt lgkmcnt(0)
	v_add_f32_e32 v114, v114, v118
	v_add_f32_e32 v116, v116, v119
	v_mov_b32_e32 v120, 0x358637bd
	s_mov_b32 s2, 0x3c800000
	v_fma_f32 v114, v114, s2, v120
	v_fma_f32 v116, v116, s2, v120
	v_mul_f32_e32 v118, 0x4b800000, v114
	v_cmp_gt_f32_e32 vcc, s3, v114
	s_nop 1
	v_cndmask_b32_e32 v118, v114, v118, vcc
	v_rsq_f32_e32 v118, v118
	s_nop 0
	v_mul_f32_e32 v122, 0x45800000, v118
	v_cndmask_b32_e32 v122, v118, v122, vcc
	v_mul_f32_e32 v119, 0x4b800000, v116
	v_cmp_gt_f32_e32 vcc, s3, v116
	s_nop 1
	v_cndmask_b32_e32 v119, v116, v119, vcc
	v_rsq_f32_e32 v119, v119
	s_nop 0
	v_mul_f32_e32 v124, 0x45800000, v119
	v_cndmask_b32_e32 v124, v119, v124, vcc
	v_mul_f32_e32 v122, s43, v122
	v_mul_f32_e32 v124, s43, v124
	s_waitcnt vmcnt(8)
	v_pk_mul_f32 v[126:127], v[194:195], v[122:123] op_sel_hi:[1,0]
	v_pk_mul_f32 v[110:111], v[110:111], v[126:127]
	v_pk_mul_f32 v[126:127], v[196:197], v[122:123] op_sel_hi:[1,0]
	v_pk_mul_f32 v[112:113], v[112:113], v[126:127]
	v_pk_mul_f32 v[126:127], v[198:199], v[122:123] op_sel_hi:[1,0]
	v_pk_mul_f32 v[106:107], v[106:107], v[126:127]
	v_pk_mul_f32 v[126:127], v[200:201], v[122:123] op_sel_hi:[1,0]
	v_pk_mul_f32 v[108:109], v[108:109], v[126:127]
	v_pk_mul_f32 v[126:127], v[202:203], v[122:123] op_sel_hi:[1,0]
	v_pk_mul_f32 v[98:99], v[98:99], v[126:127]
	v_pk_mul_f32 v[126:127], v[204:205], v[122:123] op_sel_hi:[1,0]
	v_pk_mul_f32 v[100:101], v[100:101], v[126:127]
	v_pk_mul_f32 v[126:127], v[206:207], v[122:123] op_sel_hi:[1,0]
	v_pk_mul_f32 v[90:91], v[90:91], v[126:127]
	v_pk_mul_f32 v[126:127], v[208:209], v[122:123] op_sel_hi:[1,0]
	v_pk_mul_f32 v[92:93], v[92:93], v[126:127]
	v_pk_mul_f32 v[126:127], v[194:195], v[124:125] op_sel_hi:[1,0]
	v_pk_mul_f32 v[102:103], v[102:103], v[126:127]
	v_pk_mul_f32 v[126:127], v[196:197], v[124:125] op_sel_hi:[1,0]
	v_pk_mul_f32 v[104:105], v[104:105], v[126:127]
	v_pk_mul_f32 v[126:127], v[198:199], v[124:125] op_sel_hi:[1,0]
	v_pk_mul_f32 v[94:95], v[94:95], v[126:127]
	v_pk_mul_f32 v[126:127], v[200:201], v[124:125] op_sel_hi:[1,0]
	v_pk_mul_f32 v[96:97], v[96:97], v[126:127]
	v_pk_mul_f32 v[126:127], v[202:203], v[124:125] op_sel_hi:[1,0]
	v_pk_mul_f32 v[86:87], v[86:87], v[126:127]
	v_pk_mul_f32 v[126:127], v[204:205], v[124:125] op_sel_hi:[1,0]
	v_pk_mul_f32 v[88:89], v[88:89], v[126:127]
	v_pk_mul_f32 v[126:127], v[206:207], v[124:125] op_sel_hi:[1,0]
	v_pk_mul_f32 v[82:83], v[82:83], v[126:127]
	v_pk_mul_f32 v[126:127], v[208:209], v[124:125] op_sel_hi:[1,0]
	v_pk_mul_f32 v[84:85], v[84:85], v[126:127]
	s_cmp_eq_u32 s42, 0
	s_cbranch_scc1 .Lea_pack_01
	s_waitcnt vmcnt(0)
	v_mul_f32_e32 v126, v106, v219
	v_mul_f32_e32 v127, v110, v219
	v_fma_f32 v110, v110, v218, -v126
	v_fma_f32 v106, v106, v218, v127
	v_mul_f32_e32 v126, v107, v221
	v_mul_f32_e32 v127, v111, v221
	v_fma_f32 v111, v111, v220, -v126
	v_fma_f32 v107, v107, v220, v127
	v_mul_f32_e32 v126, v108, v223
	v_mul_f32_e32 v127, v112, v223
	v_fma_f32 v112, v112, v222, -v126
	v_fma_f32 v108, v108, v222, v127
	v_mul_f32_e32 v126, v109, v225
	v_mul_f32_e32 v127, v113, v225
	v_fma_f32 v113, v113, v224, -v126
	v_fma_f32 v109, v109, v224, v127
	v_mul_f32_e32 v126, v90, v227
	v_mul_f32_e32 v127, v98, v227
	v_fma_f32 v98, v98, v226, -v126
	v_fma_f32 v90, v90, v226, v127
	v_mul_f32_e32 v126, v91, v229
	v_mul_f32_e32 v127, v99, v229
	v_fma_f32 v99, v99, v228, -v126
	v_fma_f32 v91, v91, v228, v127
	v_mul_f32_e32 v126, v92, v231
	v_mul_f32_e32 v127, v100, v231
	v_fma_f32 v100, v100, v230, -v126
	v_fma_f32 v92, v92, v230, v127
	v_mul_f32_e32 v126, v93, v233
	v_mul_f32_e32 v127, v101, v233
	v_fma_f32 v101, v101, v232, -v126
	v_fma_f32 v93, v93, v232, v127
	v_mul_f32_e32 v126, v94, v219
	v_mul_f32_e32 v127, v102, v219
	v_fma_f32 v102, v102, v218, -v126
	v_fma_f32 v94, v94, v218, v127
	v_mul_f32_e32 v126, v95, v221
	v_mul_f32_e32 v127, v103, v221
	v_fma_f32 v103, v103, v220, -v126
	v_fma_f32 v95, v95, v220, v127
	v_mul_f32_e32 v126, v96, v223
	v_mul_f32_e32 v127, v104, v223
	v_fma_f32 v104, v104, v222, -v126
	v_fma_f32 v96, v96, v222, v127
	v_mul_f32_e32 v126, v97, v225
	v_mul_f32_e32 v127, v105, v225
	v_fma_f32 v105, v105, v224, -v126
	v_fma_f32 v97, v97, v224, v127
	v_mul_f32_e32 v126, v82, v235
	v_mul_f32_e32 v127, v86, v235
	v_fma_f32 v86, v86, v234, -v126
	v_fma_f32 v82, v82, v234, v127
	v_mul_f32_e32 v126, v83, v237
	v_mul_f32_e32 v127, v87, v237
	v_fma_f32 v87, v87, v236, -v126
	v_fma_f32 v83, v83, v236, v127
	v_mul_f32_e32 v126, v84, v243
	v_mul_f32_e32 v127, v88, v243
	v_fma_f32 v88, v88, v242, -v126
	v_fma_f32 v84, v84, v242, v127
	v_mul_f32_e32 v126, v85, v245
	v_mul_f32_e32 v127, v89, v245
	v_fma_f32 v89, v89, v244, -v126
	v_fma_f32 v85, v85, v244, v127
	s_branch .Lea_pack_01
; DI void phaseA_tile(const Params& p0, int l, int ft, int mt, char* lds) {
;     ...
;     for (int gp = 0; gp < 2; ++gp) {
;       float v[2][4][4];
; #pragma unroll
;       for (int n = 0; n < 2; ++n)
; #pragma unroll
;         for (int m = 0; m < 4; ++m)
; #pragma unroll
;           for (int j = 0; j < 4; ++j) v[n][m][j] = acc[ai][gp][m][n][j] * rstd[gp * 2 + n] + bv[m][j];
;     ...
;       if (kind == 3) {
; #pragma unroll
;         for (int n = 0; n < 2; ++n) {
;           const int kraw = (is_ctx ? SEQ : 0) + s_base + tl[gp * 2 + n];
;           const int k16 = kraw & 15;
;           const int kidx = (kraw & ~15) | ((k16 & 3) | ((k16 & 4) << 1) | ((k16 & 8) >> 1));
; #pragma unroll
;           for (int m = 0; m < 4; ++m)
; #pragma unroll
;             for (int j = 0; j < 4; ++j) {
;               const int d = m * 16 + fq * 4 + j;
;               const unsigned u = pk2(v[n][m][j], 0.f);
;               vtb[(size_t)d * KEYS + kidx] = (bf16_t)(u & 0xffffu);
;             }
;         }
;       } else {
; #pragma unroll
;         for (int n = 0; n < 2; ++n) {
;           const int tlv = tl[gp * 2 + n];
; #pragma unroll
;           for (int m = 0; m < 4; ++m) {
;             u32x2 o;
;             o[0] = pk2(v[n][m][0], v[n][m][1]);
;             o[1] = pk2(v[n][m][2], v[n][m][3]);
;             const int fl = ai * 128 + wr * 64 + m * 16 + fq * 4;
;             *(u32x2*)(lds + tlv * 512 + (((fl >> 3) ^ (tlv & 31)) << 4) + ((fl >> 2) & 1) * 8) = o;
;           }
;         }
;       }
.Lea_n2_01:
	s_cmp_eq_u32 s40, 3
	s_cbranch_scc0 .Lea_pack_01
	s_lshl_b32 s14, s39, 1
	s_lshl_b32 s15, s39, 2
	s_add_i32 s15, s15, 0
	s_cmp_eq_u32 s68, 2
	s_cselect_b32 s12, s10, s34
	s_cselect_b32 s13, s11, s35
	s_cselect_b32 s14, s14, s15
	s_mul_i32 s15, s14, 0x48000
	s_mul_hi_u32 s14, s14, 0x48000
	s_add_u32 s12, s12, s15
	s_addc_u32 s13, s13, s14
	s_add_i32 s14, s74, s69
	s_lshl_b32 s14, s14, 1
	s_add_u32 s12, s12, s14
	s_addc_u32 s13, s13, 0
	v_cvt_pk_bf16_f32 v114, v110, v111
	v_cvt_pk_bf16_f32 v115, v102, v103
	v_add_u32_e32 v116, 0x0, v134
	v_add_u32_e32 v117, 0x1200, v134
	global_store_short v116, v114, s[12:13] offset:256
	global_store_short_d16_hi v117, v114, s[12:13] offset:256
	global_store_short v116, v115, s[12:13] offset:288
	global_store_short_d16_hi v117, v115, s[12:13] offset:288
	v_cvt_pk_bf16_f32 v114, v112, v113
	v_cvt_pk_bf16_f32 v115, v104, v105
	v_add_u32_e32 v116, 0x2400, v134
	v_add_u32_e32 v117, 0x3600, v134
	global_store_short v116, v114, s[12:13] offset:256
	global_store_short_d16_hi v117, v114, s[12:13] offset:256
	global_store_short v116, v115, s[12:13] offset:288
	global_store_short_d16_hi v117, v115, s[12:13] offset:288
	v_cvt_pk_bf16_f32 v114, v106, v107
	v_cvt_pk_bf16_f32 v115, v94, v95
	v_add_u32_e32 v116, 0x12000, v134
	v_add_u32_e32 v117, 0x13200, v134
	global_store_short v116, v114, s[12:13] offset:256
	global_store_short_d16_hi v117, v114, s[12:13] offset:256
	global_store_short v116, v115, s[12:13] offset:288
	global_store_short_d16_hi v117, v115, s[12:13] offset:288
	v_cvt_pk_bf16_f32 v114, v108, v109
	v_cvt_pk_bf16_f32 v115, v96, v97
	v_add_u32_e32 v116, 0x14400, v134
	v_add_u32_e32 v117, 0x15600, v134
	global_store_short v116, v114, s[12:13] offset:256
	global_store_short_d16_hi v117, v114, s[12:13] offset:256
	global_store_short v116, v115, s[12:13] offset:288
	global_store_short_d16_hi v117, v115, s[12:13] offset:288
	v_cvt_pk_bf16_f32 v114, v98, v99
	v_cvt_pk_bf16_f32 v115, v86, v87
	v_add_u32_e32 v116, 0x24000, v134
	v_add_u32_e32 v117, 0x25200, v134
	global_store_short v116, v114, s[12:13] offset:256
	global_store_short_d16_hi v117, v114, s[12:13] offset:256
	global_store_short v116, v115, s[12:13] offset:288
	global_store_short_d16_hi v117, v115, s[12:13] offset:288
	v_cvt_pk_bf16_f32 v114, v100, v101
	v_cvt_pk_bf16_f32 v115, v88, v89
	v_add_u32_e32 v116, 0x26400, v134
	v_add_u32_e32 v117, 0x27600, v134
	global_store_short v116, v114, s[12:13] offset:256
	global_store_short_d16_hi v117, v114, s[12:13] offset:256
	global_store_short v116, v115, s[12:13] offset:288
	global_store_short_d16_hi v117, v115, s[12:13] offset:288
	v_cvt_pk_bf16_f32 v114, v90, v91
	v_cvt_pk_bf16_f32 v115, v82, v83
	v_add_u32_e32 v116, 0x36000, v134
	v_add_u32_e32 v117, 0x37200, v134
	global_store_short v116, v114, s[12:13] offset:256
	global_store_short_d16_hi v117, v114, s[12:13] offset:256
	global_store_short v116, v115, s[12:13] offset:288
	global_store_short_d16_hi v117, v115, s[12:13] offset:288
	v_cvt_pk_bf16_f32 v114, v92, v93
	v_cvt_pk_bf16_f32 v115, v84, v85
	v_add_u32_e32 v116, 0x38400, v134
	v_add_u32_e32 v117, 0x39600, v134
	global_store_short v116, v114, s[12:13] offset:256
	global_store_short_d16_hi v117, v114, s[12:13] offset:256
	global_store_short v116, v115, s[12:13] offset:288
	global_store_short_d16_hi v117, v115, s[12:13] offset:288
	s_branch .Lea_done_01
.Lea_pack_01:
	v_cvt_pk_bf16_f32 v110, v110, v111
	v_cvt_pk_bf16_f32 v111, v112, v113
	v_cvt_pk_bf16_f32 v106, v106, v107
	v_cvt_pk_bf16_f32 v107, v108, v109
	v_cvt_pk_bf16_f32 v98, v98, v99
	v_cvt_pk_bf16_f32 v99, v100, v101
	v_cvt_pk_bf16_f32 v90, v90, v91
	v_cvt_pk_bf16_f32 v91, v92, v93
	v_cvt_pk_bf16_f32 v102, v102, v103
	v_cvt_pk_bf16_f32 v103, v104, v105
	v_cvt_pk_bf16_f32 v94, v94, v95
	v_cvt_pk_bf16_f32 v95, v96, v97
	v_cvt_pk_bf16_f32 v86, v86, v87
	v_cvt_pk_bf16_f32 v87, v88, v89
	v_cvt_pk_bf16_f32 v82, v82, v83
	v_cvt_pk_bf16_f32 v83, v84, v85
	ds_write_b64 v130, v[110:111]
	ds_write_b64 v131, v[106:107]
	ds_write_b64 v132, v[98:99]
	ds_write_b64 v133, v[90:91]
	ds_write_b64 v130, v[102:103] offset:8448
	ds_write_b64 v131, v[94:95] offset:8448
	ds_write_b64 v132, v[86:87] offset:8448
	ds_write_b64 v133, v[82:83] offset:8448
.Lea_done_01:
	v_pk_fma_f32 v[30:31], v[30:31], v[246:247], v[146:147] op_sel_hi:[1,0,1]
	v_pk_fma_f32 v[32:33], v[32:33], v[246:247], v[148:149] op_sel_hi:[1,0,1]
	v_pk_fma_f32 v[26:27], v[26:27], v[246:247], v[150:151] op_sel_hi:[1,0,1]
	v_pk_fma_f32 v[28:29], v[28:29], v[246:247], v[152:153] op_sel_hi:[1,0,1]
	v_pk_fma_f32 v[18:19], v[18:19], v[246:247], v[154:155] op_sel_hi:[1,0,1]
	v_pk_fma_f32 v[20:21], v[20:21], v[246:247], v[156:157] op_sel_hi:[1,0,1]
	v_pk_fma_f32 v[10:11], v[10:11], v[246:247], v[158:159] op_sel_hi:[1,0,1]
	v_pk_fma_f32 v[12:13], v[12:13], v[246:247], v[160:161] op_sel_hi:[1,0,1]
	v_pk_fma_f32 v[22:23], v[22:23], v[248:249], v[146:147] op_sel_hi:[1,0,1]
	v_pk_fma_f32 v[24:25], v[24:25], v[248:249], v[148:149] op_sel_hi:[1,0,1]
	v_pk_fma_f32 v[14:15], v[14:15], v[248:249], v[150:151] op_sel_hi:[1,0,1]
	v_pk_fma_f32 v[16:17], v[16:17], v[248:249], v[152:153] op_sel_hi:[1,0,1]
	v_pk_fma_f32 v[6:7], v[6:7], v[248:249], v[154:155] op_sel_hi:[1,0,1]
	v_pk_fma_f32 v[8:9], v[8:9], v[248:249], v[156:157] op_sel_hi:[1,0,1]
	v_pk_fma_f32 v[2:3], v[2:3], v[248:249], v[158:159] op_sel_hi:[1,0,1]
	v_pk_fma_f32 v[4:5], v[4:5], v[248:249], v[160:161] op_sel_hi:[1,0,1]
	s_cmp_eq_u32 s41, 1
	s_cbranch_scc0 .Lea_n1_11
; DI float silu_f(float v) { return v * __builtin_amdgcn_rcpf(1.f + __expf(-v)); }
; DI void phaseA_tile(const Params& p0, int l, int ft, int mt, char* lds) {
;     ...
;       if (kind == 1) {
; #pragma unroll
;         for (int n = 0; n < 2; ++n)
; #pragma unroll
;           for (int m = 0; m < 4; ++m)
; #pragma unroll
;             for (int j = 0; j < 4; ++j) v[n][m][j] = silu_f(v[n][m][j]);
	v_pk_mul_f32 v[114:115], v[30:31], s[70:71] op_sel_hi:[1,0]
	v_pk_mul_f32 v[116:117], v[32:33], s[70:71] op_sel_hi:[1,0]
	v_pk_mul_f32 v[118:119], v[26:27], s[70:71] op_sel_hi:[1,0]
	v_pk_mul_f32 v[120:121], v[28:29], s[70:71] op_sel_hi:[1,0]
	v_exp_f32_e32 v114, v114
	v_exp_f32_e32 v115, v115
	v_exp_f32_e32 v116, v116
	v_exp_f32_e32 v117, v117
	v_exp_f32_e32 v118, v118
	v_exp_f32_e32 v119, v119
	v_exp_f32_e32 v120, v120
	v_exp_f32_e32 v121, v121
	v_pk_add_f32 v[114:115], v[114:115], s[70:71] op_sel:[0,1] op_sel_hi:[1,1]
	v_pk_add_f32 v[116:117], v[116:117], s[70:71] op_sel:[0,1] op_sel_hi:[1,1]
	v_pk_add_f32 v[118:119], v[118:119], s[70:71] op_sel:[0,1] op_sel_hi:[1,1]
	v_pk_add_f32 v[120:121], v[120:121], s[70:71] op_sel:[0,1] op_sel_hi:[1,1]
	v_rcp_f32_e32 v114, v114
	v_rcp_f32_e32 v115, v115
	v_rcp_f32_e32 v116, v116
	v_rcp_f32_e32 v117, v117
	v_rcp_f32_e32 v118, v118
	v_rcp_f32_e32 v119, v119
	v_rcp_f32_e32 v120, v120
	v_rcp_f32_e32 v121, v121
	s_nop 0
	v_pk_mul_f32 v[30:31], v[30:31], v[114:115]
	v_pk_mul_f32 v[32:33], v[32:33], v[116:117]
	v_pk_mul_f32 v[26:27], v[26:27], v[118:119]
	v_pk_mul_f32 v[28:29], v[28:29], v[120:121]
	v_pk_mul_f32 v[114:115], v[18:19], s[70:71] op_sel_hi:[1,0]
	v_pk_mul_f32 v[116:117], v[20:21], s[70:71] op_sel_hi:[1,0]
	v_pk_mul_f32 v[118:119], v[10:11], s[70:71] op_sel_hi:[1,0]
	v_pk_mul_f32 v[120:121], v[12:13], s[70:71] op_sel_hi:[1,0]
	v_exp_f32_e32 v114, v114
	v_exp_f32_e32 v115, v115
	v_exp_f32_e32 v116, v116
	v_exp_f32_e32 v117, v117
	v_exp_f32_e32 v118, v118
	v_exp_f32_e32 v119, v119
	v_exp_f32_e32 v120, v120
	v_exp_f32_e32 v121, v121
	v_pk_add_f32 v[114:115], v[114:115], s[70:71] op_sel:[0,1] op_sel_hi:[1,1]
	v_pk_add_f32 v[116:117], v[116:117], s[70:71] op_sel:[0,1] op_sel_hi:[1,1]
	v_pk_add_f32 v[118:119], v[118:119], s[70:71] op_sel:[0,1] op_sel_hi:[1,1]
	v_pk_add_f32 v[120:121], v[120:121], s[70:71] op_sel:[0,1] op_sel_hi:[1,1]
	v_rcp_f32_e32 v114, v114
	v_rcp_f32_e32 v115, v115
	v_rcp_f32_e32 v116, v116
	v_rcp_f32_e32 v117, v117
	v_rcp_f32_e32 v118, v118
	v_rcp_f32_e32 v119, v119
	v_rcp_f32_e32 v120, v120
	v_rcp_f32_e32 v121, v121
	s_nop 0
	v_pk_mul_f32 v[18:19], v[18:19], v[114:115]
	v_pk_mul_f32 v[20:21], v[20:21], v[116:117]
	v_pk_mul_f32 v[10:11], v[10:11], v[118:119]
	v_pk_mul_f32 v[12:13], v[12:13], v[120:121]
	v_pk_mul_f32 v[114:115], v[22:23], s[70:71] op_sel_hi:[1,0]
	v_pk_mul_f32 v[116:117], v[24:25], s[70:71] op_sel_hi:[1,0]
	v_pk_mul_f32 v[118:119], v[14:15], s[70:71] op_sel_hi:[1,0]
	v_pk_mul_f32 v[120:121], v[16:17], s[70:71] op_sel_hi:[1,0]
	v_exp_f32_e32 v114, v114
	v_exp_f32_e32 v115, v115
	v_exp_f32_e32 v116, v116
	v_exp_f32_e32 v117, v117
	v_exp_f32_e32 v118, v118
	v_exp_f32_e32 v119, v119
	v_exp_f32_e32 v120, v120
	v_exp_f32_e32 v121, v121
	v_pk_add_f32 v[114:115], v[114:115], s[70:71] op_sel:[0,1] op_sel_hi:[1,1]
	v_pk_add_f32 v[116:117], v[116:117], s[70:71] op_sel:[0,1] op_sel_hi:[1,1]
	v_pk_add_f32 v[118:119], v[118:119], s[70:71] op_sel:[0,1] op_sel_hi:[1,1]
	v_pk_add_f32 v[120:121], v[120:121], s[70:71] op_sel:[0,1] op_sel_hi:[1,1]
	v_rcp_f32_e32 v114, v114
	v_rcp_f32_e32 v115, v115
	v_rcp_f32_e32 v116, v116
	v_rcp_f32_e32 v117, v117
	v_rcp_f32_e32 v118, v118
	v_rcp_f32_e32 v119, v119
	v_rcp_f32_e32 v120, v120
	v_rcp_f32_e32 v121, v121
	s_nop 0
	v_pk_mul_f32 v[22:23], v[22:23], v[114:115]
	v_pk_mul_f32 v[24:25], v[24:25], v[116:117]
	v_pk_mul_f32 v[14:15], v[14:15], v[118:119]
	v_pk_mul_f32 v[16:17], v[16:17], v[120:121]
	v_pk_mul_f32 v[114:115], v[6:7], s[70:71] op_sel_hi:[1,0]
	v_pk_mul_f32 v[116:117], v[8:9], s[70:71] op_sel_hi:[1,0]
	v_pk_mul_f32 v[118:119], v[2:3], s[70:71] op_sel_hi:[1,0]
	v_pk_mul_f32 v[120:121], v[4:5], s[70:71] op_sel_hi:[1,0]
	v_exp_f32_e32 v114, v114
	v_exp_f32_e32 v115, v115
	v_exp_f32_e32 v116, v116
	v_exp_f32_e32 v117, v117
	v_exp_f32_e32 v118, v118
	v_exp_f32_e32 v119, v119
	v_exp_f32_e32 v120, v120
	v_exp_f32_e32 v121, v121
	v_pk_add_f32 v[114:115], v[114:115], s[70:71] op_sel:[0,1] op_sel_hi:[1,1]
	v_pk_add_f32 v[116:117], v[116:117], s[70:71] op_sel:[0,1] op_sel_hi:[1,1]
	v_pk_add_f32 v[118:119], v[118:119], s[70:71] op_sel:[0,1] op_sel_hi:[1,1]
	v_pk_add_f32 v[120:121], v[120:121], s[70:71] op_sel:[0,1] op_sel_hi:[1,1]
	v_rcp_f32_e32 v114, v114
	v_rcp_f32_e32 v115, v115
	v_rcp_f32_e32 v116, v116
	v_rcp_f32_e32 v117, v117
	v_rcp_f32_e32 v118, v118
	v_rcp_f32_e32 v119, v119
	v_rcp_f32_e32 v120, v120
	v_rcp_f32_e32 v121, v121
	s_nop 0
	v_pk_mul_f32 v[6:7], v[6:7], v[114:115]
	v_pk_mul_f32 v[8:9], v[8:9], v[116:117]
	v_pk_mul_f32 v[2:3], v[2:3], v[118:119]
	v_pk_mul_f32 v[4:5], v[4:5], v[120:121]
	s_branch .Lea_pack_11
; DI void phaseA_tile(const Params& p0, int l, int ft, int mt, char* lds) {
;     ...
;       } else if (kind == 2) {
;         f32x4 gv[4];
; #pragma unroll
;         for (int m = 0; m < 4; ++m) gv[m] = *(const f32x4*)(gain + m * 16 + fq * 4);
; #pragma unroll
;         for (int n = 0; n < 2; ++n) {
;           float ss = 0.f;
; #pragma unroll
;           for (int m = 0; m < 4; ++m)
; #pragma unroll
;             for (int j = 0; j < 4; ++j) ss += v[n][m][j] * v[n][m][j];
;           ss += __shfl_xor(ss, 16);
;           ss += __shfl_xor(ss, 32);
;           const float rn = rsqrtf(ss * (1.f / 64.f) + EPS) * sc;
; #pragma unroll
;           for (int m = 0; m < 4; ++m)
; #pragma unroll
;             for (int j = 0; j < 4; ++j) v[n][m][j] *= rn * gv[m][j];
;         }
;         if (do_rope) {
; #pragma unroll
;           for (int n = 0; n < 2; ++n) {
;             f32x4 cs4[2][2];
;             const int s = s_base + tl[gp * 2 + n];
; #pragma unroll
;             for (int hf = 0; hf < 2; ++hf) {
;               const int pos = hf == 0 ? (s >> 6) : (s & 63);
;               const float* tb = p.rope + (size_t)pos * 32 + fq * 8;
;               cs4[hf][0] = *(const f32x4*)(tb);
;               cs4[hf][1] = *(const f32x4*)(tb + 4);
;             }
; #pragma unroll
;             for (int hf = 0; hf < 2; ++hf)
; #pragma unroll
;               for (int j = 0; j < 4; ++j) {
;                 const float c = cs4[hf][j >> 1][(j & 1) * 2], sn = cs4[hf][j >> 1][(j & 1) * 2 + 1];
;                 const float x1 = v[n][2 * hf][j], x2 = v[n][2 * hf + 1][j];
;                 v[n][2 * hf][j] = x1 * c - x2 * sn;
;                 v[n][2 * hf + 1][j] = x2 * c + x1 * sn;
;               }
;           }
;         }
.Lea_n1_11:
	s_cmp_eq_u32 s41, 2
	s_cbranch_scc0 .Lea_n2_11
	v_pk_mul_f32 v[114:115], v[30:31], v[30:31]
	v_pk_fma_f32 v[114:115], v[32:33], v[32:33], v[114:115]
	v_pk_fma_f32 v[114:115], v[26:27], v[26:27], v[114:115]
	v_pk_fma_f32 v[114:115], v[28:29], v[28:29], v[114:115]
	v_pk_fma_f32 v[114:115], v[18:19], v[18:19], v[114:115]
	v_pk_fma_f32 v[114:115], v[20:21], v[20:21], v[114:115]
	v_pk_fma_f32 v[114:115], v[10:11], v[10:11], v[114:115]
	v_pk_fma_f32 v[114:115], v[12:13], v[12:13], v[114:115]
	v_pk_mul_f32 v[116:117], v[22:23], v[22:23]
	v_pk_fma_f32 v[116:117], v[24:25], v[24:25], v[116:117]
	v_pk_fma_f32 v[116:117], v[14:15], v[14:15], v[116:117]
	v_pk_fma_f32 v[116:117], v[16:17], v[16:17], v[116:117]
	v_pk_fma_f32 v[116:117], v[6:7], v[6:7], v[116:117]
	v_pk_fma_f32 v[116:117], v[8:9], v[8:9], v[116:117]
	v_pk_fma_f32 v[116:117], v[2:3], v[2:3], v[116:117]
	v_pk_fma_f32 v[116:117], v[4:5], v[4:5], v[116:117]
	v_add_f32_e32 v114, v114, v115
	v_add_f32_e32 v116, v116, v117
	ds_bpermute_b32 v118, v135, v114
	ds_bpermute_b32 v119, v135, v116
	s_waitcnt lgkmcnt(0)
	v_add_f32_e32 v114, v114, v118
	v_add_f32_e32 v116, v116, v119
	ds_bpermute_b32 v118, v136, v114
	ds_bpermute_b32 v119, v136, v116
	s_waitcnt lgkmcnt(0)
	v_add_f32_e32 v114, v114, v118
	v_add_f32_e32 v116, v116, v119
	v_mov_b32_e32 v120, 0x358637bd
	s_mov_b32 s2, 0x3c800000
	v_fma_f32 v114, v114, s2, v120
	v_fma_f32 v116, v116, s2, v120
	v_mul_f32_e32 v118, 0x4b800000, v114
	v_cmp_gt_f32_e32 vcc, s3, v114
	s_nop 1
	v_cndmask_b32_e32 v118, v114, v118, vcc
	v_rsq_f32_e32 v118, v118
	s_nop 0
	v_mul_f32_e32 v122, 0x45800000, v118
	v_cndmask_b32_e32 v122, v118, v122, vcc
	v_mul_f32_e32 v119, 0x4b800000, v116
	v_cmp_gt_f32_e32 vcc, s3, v116
	s_nop 1
	v_cndmask_b32_e32 v119, v116, v119, vcc
	v_rsq_f32_e32 v119, v119
	s_nop 0
	v_mul_f32_e32 v124, 0x45800000, v119
	v_cndmask_b32_e32 v124, v119, v124, vcc
	v_mul_f32_e32 v122, s43, v122
	v_mul_f32_e32 v124, s43, v124
	s_waitcnt vmcnt(8)
	v_pk_mul_f32 v[126:127], v[194:195], v[122:123] op_sel_hi:[1,0]
	v_pk_mul_f32 v[30:31], v[30:31], v[126:127]
	v_pk_mul_f32 v[126:127], v[196:197], v[122:123] op_sel_hi:[1,0]
	v_pk_mul_f32 v[32:33], v[32:33], v[126:127]
	v_pk_mul_f32 v[126:127], v[198:199], v[122:123] op_sel_hi:[1,0]
	v_pk_mul_f32 v[26:27], v[26:27], v[126:127]
	v_pk_mul_f32 v[126:127], v[200:201], v[122:123] op_sel_hi:[1,0]
	v_pk_mul_f32 v[28:29], v[28:29], v[126:127]
	v_pk_mul_f32 v[126:127], v[202:203], v[122:123] op_sel_hi:[1,0]
	v_pk_mul_f32 v[18:19], v[18:19], v[126:127]
	v_pk_mul_f32 v[126:127], v[204:205], v[122:123] op_sel_hi:[1,0]
	v_pk_mul_f32 v[20:21], v[20:21], v[126:127]
	v_pk_mul_f32 v[126:127], v[206:207], v[122:123] op_sel_hi:[1,0]
	v_pk_mul_f32 v[10:11], v[10:11], v[126:127]
	v_pk_mul_f32 v[126:127], v[208:209], v[122:123] op_sel_hi:[1,0]
	v_pk_mul_f32 v[12:13], v[12:13], v[126:127]
	v_pk_mul_f32 v[126:127], v[194:195], v[124:125] op_sel_hi:[1,0]
	v_pk_mul_f32 v[22:23], v[22:23], v[126:127]
	v_pk_mul_f32 v[126:127], v[196:197], v[124:125] op_sel_hi:[1,0]
	v_pk_mul_f32 v[24:25], v[24:25], v[126:127]
	v_pk_mul_f32 v[126:127], v[198:199], v[124:125] op_sel_hi:[1,0]
	v_pk_mul_f32 v[14:15], v[14:15], v[126:127]
	v_pk_mul_f32 v[126:127], v[200:201], v[124:125] op_sel_hi:[1,0]
	v_pk_mul_f32 v[16:17], v[16:17], v[126:127]
	v_pk_mul_f32 v[126:127], v[202:203], v[124:125] op_sel_hi:[1,0]
	v_pk_mul_f32 v[6:7], v[6:7], v[126:127]
	v_pk_mul_f32 v[126:127], v[204:205], v[124:125] op_sel_hi:[1,0]
	v_pk_mul_f32 v[8:9], v[8:9], v[126:127]
	v_pk_mul_f32 v[126:127], v[206:207], v[124:125] op_sel_hi:[1,0]
	v_pk_mul_f32 v[2:3], v[2:3], v[126:127]
	v_pk_mul_f32 v[126:127], v[208:209], v[124:125] op_sel_hi:[1,0]
	v_pk_mul_f32 v[4:5], v[4:5], v[126:127]
	s_cmp_eq_u32 s42, 0
	s_cbranch_scc1 .Lea_pack_11
	s_waitcnt vmcnt(0)
	v_mul_f32_e32 v126, v26, v219
	v_mul_f32_e32 v127, v30, v219
	v_fma_f32 v30, v30, v218, -v126
	v_fma_f32 v26, v26, v218, v127
	v_mul_f32_e32 v126, v27, v221
	v_mul_f32_e32 v127, v31, v221
	v_fma_f32 v31, v31, v220, -v126
	v_fma_f32 v27, v27, v220, v127
	v_mul_f32_e32 v126, v28, v223
	v_mul_f32_e32 v127, v32, v223
	v_fma_f32 v32, v32, v222, -v126
	v_fma_f32 v28, v28, v222, v127
	v_mul_f32_e32 v126, v29, v225
	v_mul_f32_e32 v127, v33, v225
	v_fma_f32 v33, v33, v224, -v126
	v_fma_f32 v29, v29, v224, v127
	v_mul_f32_e32 v126, v10, v227
	v_mul_f32_e32 v127, v18, v227
	v_fma_f32 v18, v18, v226, -v126
	v_fma_f32 v10, v10, v226, v127
	v_mul_f32_e32 v126, v11, v229
	v_mul_f32_e32 v127, v19, v229
	v_fma_f32 v19, v19, v228, -v126
	v_fma_f32 v11, v11, v228, v127
	v_mul_f32_e32 v126, v12, v231
	v_mul_f32_e32 v127, v20, v231
	v_fma_f32 v20, v20, v230, -v126
	v_fma_f32 v12, v12, v230, v127
	v_mul_f32_e32 v126, v13, v233
	v_mul_f32_e32 v127, v21, v233
	v_fma_f32 v21, v21, v232, -v126
	v_fma_f32 v13, v13, v232, v127
	v_mul_f32_e32 v126, v14, v219
	v_mul_f32_e32 v127, v22, v219
	v_fma_f32 v22, v22, v218, -v126
	v_fma_f32 v14, v14, v218, v127
	v_mul_f32_e32 v126, v15, v221
	v_mul_f32_e32 v127, v23, v221
	v_fma_f32 v23, v23, v220, -v126
	v_fma_f32 v15, v15, v220, v127
	v_mul_f32_e32 v126, v16, v223
	v_mul_f32_e32 v127, v24, v223
	v_fma_f32 v24, v24, v222, -v126
	v_fma_f32 v16, v16, v222, v127
	v_mul_f32_e32 v126, v17, v225
	v_mul_f32_e32 v127, v25, v225
	v_fma_f32 v25, v25, v224, -v126
	v_fma_f32 v17, v17, v224, v127
	v_mul_f32_e32 v126, v2, v235
	v_mul_f32_e32 v127, v6, v235
	v_fma_f32 v6, v6, v234, -v126
	v_fma_f32 v2, v2, v234, v127
	v_mul_f32_e32 v126, v3, v237
	v_mul_f32_e32 v127, v7, v237
	v_fma_f32 v7, v7, v236, -v126
	v_fma_f32 v3, v3, v236, v127
	v_mul_f32_e32 v126, v4, v243
	v_mul_f32_e32 v127, v8, v243
	v_fma_f32 v8, v8, v242, -v126
	v_fma_f32 v4, v4, v242, v127
	v_mul_f32_e32 v126, v5, v245
	v_mul_f32_e32 v127, v9, v245
	v_fma_f32 v9, v9, v244, -v126
	v_fma_f32 v5, v5, v244, v127
	s_branch .Lea_pack_11
; DI void phaseA_tile(const Params& p0, int l, int ft, int mt, char* lds) {
;     ...
;       if (kind == 3) {
; #pragma unroll
;         for (int n = 0; n < 2; ++n) {
;           const int kraw = (is_ctx ? SEQ : 0) + s_base + tl[gp * 2 + n];
;           const int k16 = kraw & 15;
;           const int kidx = (kraw & ~15) | ((k16 & 3) | ((k16 & 4) << 1) | ((k16 & 8) >> 1));
; #pragma unroll
;           for (int m = 0; m < 4; ++m)
; #pragma unroll
;             for (int j = 0; j < 4; ++j) {
;               const int d = m * 16 + fq * 4 + j;
;               const unsigned u = pk2(v[n][m][j], 0.f);
;               vtb[(size_t)d * KEYS + kidx] = (bf16_t)(u & 0xffffu);
;             }
;         }
.Lea_n2_11:
	s_cmp_eq_u32 s41, 3
	s_cbranch_scc0 .Lea_pack_11
	s_lshl_b32 s14, s39, 1
	s_lshl_b32 s15, s39, 2
	s_add_i32 s15, s15, 2
	s_cmp_eq_u32 s68, 2
	s_cselect_b32 s12, s10, s34
	s_cselect_b32 s13, s11, s35
	s_cselect_b32 s14, s14, s15
	s_mul_i32 s15, s14, 0x48000
	s_mul_hi_u32 s14, s14, 0x48000
	s_add_u32 s12, s12, s15
	s_addc_u32 s13, s13, s14
	s_add_i32 s14, s74, s69
	s_lshl_b32 s14, s14, 1
	s_add_u32 s12, s12, s14
	s_addc_u32 s13, s13, 0
	v_cvt_pk_bf16_f32 v114, v30, v31
	v_cvt_pk_bf16_f32 v115, v22, v23
	v_add_u32_e32 v116, 0x0, v134
	v_add_u32_e32 v117, 0x1200, v134
	global_store_short v116, v114, s[12:13] offset:256
	global_store_short_d16_hi v117, v114, s[12:13] offset:256
	global_store_short v116, v115, s[12:13] offset:288
	global_store_short_d16_hi v117, v115, s[12:13] offset:288
	v_cvt_pk_bf16_f32 v114, v32, v33
	v_cvt_pk_bf16_f32 v115, v24, v25
	v_add_u32_e32 v116, 0x2400, v134
	v_add_u32_e32 v117, 0x3600, v134
	global_store_short v116, v114, s[12:13] offset:256
	global_store_short_d16_hi v117, v114, s[12:13] offset:256
	global_store_short v116, v115, s[12:13] offset:288
	global_store_short_d16_hi v117, v115, s[12:13] offset:288
	v_cvt_pk_bf16_f32 v114, v26, v27
	v_cvt_pk_bf16_f32 v115, v14, v15
	v_add_u32_e32 v116, 0x12000, v134
	v_add_u32_e32 v117, 0x13200, v134
	global_store_short v116, v114, s[12:13] offset:256
	global_store_short_d16_hi v117, v114, s[12:13] offset:256
	global_store_short v116, v115, s[12:13] offset:288
	global_store_short_d16_hi v117, v115, s[12:13] offset:288
	v_cvt_pk_bf16_f32 v114, v28, v29
	v_cvt_pk_bf16_f32 v115, v16, v17
	v_add_u32_e32 v116, 0x14400, v134
	v_add_u32_e32 v117, 0x15600, v134
	global_store_short v116, v114, s[12:13] offset:256
	global_store_short_d16_hi v117, v114, s[12:13] offset:256
	global_store_short v116, v115, s[12:13] offset:288
	global_store_short_d16_hi v117, v115, s[12:13] offset:288
	v_cvt_pk_bf16_f32 v114, v18, v19
	v_cvt_pk_bf16_f32 v115, v6, v7
	v_add_u32_e32 v116, 0x24000, v134
	v_add_u32_e32 v117, 0x25200, v134
	global_store_short v116, v114, s[12:13] offset:256
	global_store_short_d16_hi v117, v114, s[12:13] offset:256
	global_store_short v116, v115, s[12:13] offset:288
	global_store_short_d16_hi v117, v115, s[12:13] offset:288
	v_cvt_pk_bf16_f32 v114, v20, v21
	v_cvt_pk_bf16_f32 v115, v8, v9
	v_add_u32_e32 v116, 0x26400, v134
	v_add_u32_e32 v117, 0x27600, v134
	global_store_short v116, v114, s[12:13] offset:256
	global_store_short_d16_hi v117, v114, s[12:13] offset:256
	global_store_short v116, v115, s[12:13] offset:288
	global_store_short_d16_hi v117, v115, s[12:13] offset:288
	v_cvt_pk_bf16_f32 v114, v10, v11
	v_cvt_pk_bf16_f32 v115, v2, v3
	v_add_u32_e32 v116, 0x36000, v134
	v_add_u32_e32 v117, 0x37200, v134
	global_store_short v116, v114, s[12:13] offset:256
	global_store_short_d16_hi v117, v114, s[12:13] offset:256
	global_store_short v116, v115, s[12:13] offset:288
	global_store_short_d16_hi v117, v115, s[12:13] offset:288
	v_cvt_pk_bf16_f32 v114, v12, v13
	v_cvt_pk_bf16_f32 v115, v4, v5
	v_add_u32_e32 v116, 0x38400, v134
	v_add_u32_e32 v117, 0x39600, v134
	global_store_short v116, v114, s[12:13] offset:256
	global_store_short_d16_hi v117, v114, s[12:13] offset:256
	global_store_short v116, v115, s[12:13] offset:288
	global_store_short_d16_hi v117, v115, s[12:13] offset:288
	s_branch .Lea_done_11
; DI void phaseA_tile(const Params& p0, int l, int ft, int mt, char* lds) {
;     ...
;       } else {
; #pragma unroll
;         for (int n = 0; n < 2; ++n) {
;           const int tlv = tl[gp * 2 + n];
; #pragma unroll
;           for (int m = 0; m < 4; ++m) {
;             u32x2 o;
;             o[0] = pk2(v[n][m][0], v[n][m][1]);
;             o[1] = pk2(v[n][m][2], v[n][m][3]);
;             const int fl = ai * 128 + wr * 64 + m * 16 + fq * 4;
;             *(u32x2*)(lds + tlv * 512 + (((fl >> 3) ^ (tlv & 31)) << 4) + ((fl >> 2) & 1) * 8) = o;
;           }
;         }
;       }
;     }
;   }
;   __syncthreads();
;   if (ft != 9) {
;     const int nch = (ft == 2) ? 16 : 32;
; #pragma unroll 4
;     for (int i = 0; i < 16; ++i) {
;       const int idx = tid + NTHREADS * i;
;       const int row = idx >> 5, c = idx & 31;
;       if (c < nch) {
;         const u32x4 val = *(const u32x4*)(lds + row * 512 + ((c ^ (row & 31)) << 4));
;         *(u32x4*)(p.P + (size_t)(m0 + row) * INW + n0 + c * 8) = val;
;       }
;     }
;   }
;   __syncthreads();
.Lea_pack_11:
	v_cvt_pk_bf16_f32 v30, v30, v31
	v_cvt_pk_bf16_f32 v31, v32, v33
	v_cvt_pk_bf16_f32 v26, v26, v27
	v_cvt_pk_bf16_f32 v27, v28, v29
	v_cvt_pk_bf16_f32 v18, v18, v19
	v_cvt_pk_bf16_f32 v19, v20, v21
	v_cvt_pk_bf16_f32 v10, v10, v11
	v_cvt_pk_bf16_f32 v11, v12, v13
	v_cvt_pk_bf16_f32 v22, v22, v23
	v_cvt_pk_bf16_f32 v23, v24, v25
	v_cvt_pk_bf16_f32 v14, v14, v15
	v_cvt_pk_bf16_f32 v15, v16, v17
	v_cvt_pk_bf16_f32 v6, v6, v7
	v_cvt_pk_bf16_f32 v7, v8, v9
	v_cvt_pk_bf16_f32 v2, v2, v3
	v_cvt_pk_bf16_f32 v3, v4, v5
	ds_write_b64 v130, v[30:31] offset:256
	ds_write_b64 v131, v[26:27] offset:256
	ds_write_b64 v132, v[18:19] offset:256
	ds_write_b64 v133, v[10:11] offset:256
	ds_write_b64 v130, v[22:23] offset:8192
	ds_write_b64 v131, v[14:15] offset:8192
	ds_write_b64 v132, v[6:7] offset:8192
	ds_write_b64 v133, v[2:3] offset:8192
.Lea_done_11:
	s_waitcnt vmcnt(0) lgkmcnt(0)
	s_barrier
	s_cmp_eq_u32 s68, 9
	s_cbranch_scc1 .Lea_end
	v_and_b32_e32 v2, 31, v251
	v_lshrrev_b32_e32 v3, 5, v251
	v_xor_b32_e32 v4, v2, v3
	v_lshlrev_b32_e32 v4, 4, v4
	v_lshl_add_u32 v4, v3, 9, v4
	v_xor_b32_e32 v5, 0x100, v4
	v_add_u32_e32 v6, 0x10000, v4
	v_add_u32_e32 v7, 0x10000, v5
	v_mul_u32_u24_e32 v8, 0x1600, v3
	v_lshl_add_u32 v8, v2, 4, v8
	ds_read_b128 v[50:53], v4
	ds_read_b128 v[54:57], v5 offset:8192
	ds_read_b128 v[58:61], v4 offset:16384
	ds_read_b128 v[62:65], v5 offset:24576
	ds_read_b128 v[66:69], v4 offset:32768
	ds_read_b128 v[70:73], v5 offset:40960
	ds_read_b128 v[74:77], v4 offset:49152
	ds_read_b128 v[78:81], v5 offset:57344
	ds_read_b128 v[82:85], v6
	ds_read_b128 v[86:89], v7 offset:8192
	ds_read_b128 v[90:93], v6 offset:16384
	ds_read_b128 v[94:97], v7 offset:24576
	ds_read_b128 v[98:101], v6 offset:32768
	ds_read_b128 v[102:105], v7 offset:40960
	ds_read_b128 v[106:109], v6 offset:49152
	ds_read_b128 v[110:113], v7 offset:57344
	s_mul_i32 s2, s0, 0x1600
	s_mul_hi_u32 s3, s0, 0x1600
	s_add_u32 s2, s8, s2
	s_addc_u32 s3, s9, s3
	s_lshl_b32 s29, s30, 1
	s_add_u32 s2, s2, s29
	s_addc_u32 s3, s3, 0
	s_cmp_eq_u32 s68, 2
	s_cbranch_scc0 .Lea_full
	v_cmp_gt_u32_e32 vcc, 16, v2
	s_nop 1
	s_and_b64 exec, exec, vcc
.Lea_full:
	s_waitcnt lgkmcnt(15)
	global_store_dwordx4 v8, v[50:53], s[2:3]
	s_add_u32 s2, s2, 0x16000
	s_addc_u32 s3, s3, 0
	s_waitcnt lgkmcnt(14)
	global_store_dwordx4 v8, v[54:57], s[2:3]
	s_add_u32 s2, s2, 0x16000
	s_addc_u32 s3, s3, 0
	s_waitcnt lgkmcnt(13)
	global_store_dwordx4 v8, v[58:61], s[2:3]
	s_add_u32 s2, s2, 0x16000
	s_addc_u32 s3, s3, 0
	s_waitcnt lgkmcnt(12)
	global_store_dwordx4 v8, v[62:65], s[2:3]
	s_add_u32 s2, s2, 0x16000
	s_addc_u32 s3, s3, 0
	s_waitcnt lgkmcnt(11)
	global_store_dwordx4 v8, v[66:69], s[2:3]
	s_add_u32 s2, s2, 0x16000
	s_addc_u32 s3, s3, 0
	s_waitcnt lgkmcnt(10)
	global_store_dwordx4 v8, v[70:73], s[2:3]
	s_add_u32 s2, s2, 0x16000
	s_addc_u32 s3, s3, 0
	s_waitcnt lgkmcnt(9)
	global_store_dwordx4 v8, v[74:77], s[2:3]
	s_add_u32 s2, s2, 0x16000
	s_addc_u32 s3, s3, 0
	s_waitcnt lgkmcnt(8)
	global_store_dwordx4 v8, v[78:81], s[2:3]
	s_add_u32 s2, s2, 0x16000
	s_addc_u32 s3, s3, 0
	s_waitcnt lgkmcnt(7)
	global_store_dwordx4 v8, v[82:85], s[2:3]
	s_add_u32 s2, s2, 0x16000
	s_addc_u32 s3, s3, 0
	s_waitcnt lgkmcnt(6)
	global_store_dwordx4 v8, v[86:89], s[2:3]
	s_add_u32 s2, s2, 0x16000
	s_addc_u32 s3, s3, 0
	s_waitcnt lgkmcnt(5)
	global_store_dwordx4 v8, v[90:93], s[2:3]
	s_add_u32 s2, s2, 0x16000
	s_addc_u32 s3, s3, 0
	s_waitcnt lgkmcnt(4)
	global_store_dwordx4 v8, v[94:97], s[2:3]
	s_add_u32 s2, s2, 0x16000
	s_addc_u32 s3, s3, 0
	s_waitcnt lgkmcnt(3)
	global_store_dwordx4 v8, v[98:101], s[2:3]
	s_add_u32 s2, s2, 0x16000
	s_addc_u32 s3, s3, 0
	s_waitcnt lgkmcnt(2)
	global_store_dwordx4 v8, v[102:105], s[2:3]
	s_add_u32 s2, s2, 0x16000
	s_addc_u32 s3, s3, 0
	s_waitcnt lgkmcnt(1)
	global_store_dwordx4 v8, v[106:109], s[2:3]
	s_add_u32 s2, s2, 0x16000
	s_addc_u32 s3, s3, 0
	s_waitcnt lgkmcnt(0)
	global_store_dwordx4 v8, v[110:113], s[2:3]
	s_mov_b64 exec, -1
.Lea_end:
	s_waitcnt lgkmcnt(0)
	s_barrier
	s_branch .LBB0_333
